# attention step loop bookkeeping trimmed by 4 instructions per step (m0 ahead of the address VALU, precomputed diagonal/window bounds, single-move pending flags)
# baseline (speedup 1.0000x reference)
; #define RING_ISSUE(SI) do { int kbi = kb0 + (SI) * 32; if (kbi > kb_last) kbi = kb_last; const int slot = (SI) % 3; \
;           const h16* srcp = wave < 4 ? kbase + (size_t)kbi * LDH + k_src_off : vT + (size_t)(kbi >> 5) * 2048 + v_src_off; \
;           __builtin_amdgcn_global_load_lds((const unsigned*)srcp, (LAS unsigned*)(ring + slot * 8192 + stage_dst), 16, 0, 0); } while (0)
; DI void attn_phase(const Params& p, const int layer, const int wid_s) {
;     ...
;       const int kb_last = qblk * 64 + 32;
;       const int kmax_w = (t0 + 15) & ~31;
; #pragma unroll 1
;       for (int br = 1; br <= 2; ++br) {
;         const h16* kbase = hb + (br == 1 ? C_KS : C_KW) + g * 64;
;         const h16* vT = (const h16*)(p.ws + (br == 1 ? OFF_VST : OFF_VWT)) + (size_t)bg * 64 * SEQ;
;         int kb0 = 0, lo_w = 0;
;         if (br == 2) { kb0 = qblk * 64 - 512; if (kb0 < 0) kb0 = 0; lo_w = t0 - 511; if (lo_w < 0) lo_w = 0; lo_w &= ~31; }
;         const int nsteps = (kb_last - kb0) / 32 + 1;
;         f32x4 O[2][4]; float l[2];
; #pragma unroll
;         for (int hp = 0; hp < 2; ++hp) { l[hp] = 0.f;
; #pragma unroll
;           for (int dt = 0; dt < 4; ++dt) O[hp][dt] = (f32x4){0.f, 0.f, 0.f, 0.f}; }
;     ...
;         asm volatile("s_waitcnt vmcnt(0)" ::: "memory");
;         __syncthreads();
;         RING_ISSUE(0); RING_ISSUE(1);
; #pragma unroll 1
;         for (int si = 0; si < nsteps; ++si) {
;           asm volatile("s_waitcnt vmcnt(1) lgkmcnt(0)" ::: "memory");
;           __builtin_amdgcn_s_barrier();
;           asm volatile("" ::: "memory");
;           RING_ISSUE(si + 2);
;           const int kb = kb0 + si * 32;
;           if (kb > kmax_w || kb < lo_w) continue;
;           if (br == 1 && kb + 31 + 128 <= t0 && __ballot((selmask >> (kb >> 6)) & 1u) == 0ull) continue;
.LBB0_349:
	s_add_i32 s39, s51, 0xffffff61
	s_add_i32 s43, s51, 0xfffffe0f
	v_add_u32_e32 v0, 0x19880, v185
	v_add_u32_e32 v64, 0x19880, v184
	v_add_u32_e32 v65, 0x19880, v183
	s_and_b64 vcc, exec, s[30:31]
	s_cbranch_vccz .Lat_ytop
	s_branch .Lat_xtop

; #define MFMA16(a, b, c) __builtin_amdgcn_mfma_f32_16x16x32_f16((a), (b), (c), 0, 0, 0)
; #define LAS __attribute__((address_space(3)))
; template <bool SEL, bool GEN>
; DI void attn_step(const KF& kv, const int kb, const int t, const int lane, const bool selbit,
;                   const LAS float* tabh, const half8 (&q)[2][2], f32x4 (&O)[2][4], const float (&nR)[2], float (&l)[2]) {
;     ...
;   half8 pf[2];
; #pragma unroll
;   for (int hp = 0; hp < 2; ++hp) {
;     f32x4 p0, p1;
; #pragma unroll
;     for (int j = 0; j < 4; ++j) { p0[j] = __builtin_amdgcn_exp2f(s[hp][0][j]); p1[j] = __builtin_amdgcn_exp2f(s[hp][1][j]); }
;     l[hp] += ((p0[0] + p0[1]) + (p0[2] + p0[3])) + ((p1[0] + p1[1]) + (p1[2] + p1[3]));
;     pf[hp] = pack8(p0, p1);
;   }
; #pragma unroll
;   for (int dt = 0; dt < 4; ++dt)
; #pragma unroll
;     for (int hp = 0; hp < 2; ++hp) O[hp][dt] = MFMA16(kv.v[dt], pf[hp], O[hp][dt]);
; DI void attn_phase(const Params& p, const int layer, const int wid_s) {
;     ...
;         for (int si = 0; si < nsteps; ++si) {
;           asm volatile("s_waitcnt vmcnt(1) lgkmcnt(0)" ::: "memory");
;           __builtin_amdgcn_s_barrier();
;           asm volatile("" ::: "memory");
;           RING_ISSUE(si + 2);
;           const int kb = kb0 + si * 32;
;           if (kb > kmax_w || kb < lo_w) continue;
;           if (br == 1 && kb + 31 + 128 <= t0 && __ballot((selmask >> (kb >> 6)) & 1u) == 0ull) continue;
;           LAS unsigned char* slotp = ring + (si % 3) * 8192;
;           KF kv;
; #pragma unroll
;           for (int kt = 0; kt < 2; ++kt)
; #pragma unroll
;             for (int ks = 0; ks < 2; ++ks) kv.k[kt][ks] = *(const LAS half8*)(slotp + kread[kt][ks]);
; #pragma unroll
;           for (int dt = 0; dt < 4; ++dt) kv.v[dt] = *(const LAS half8*)(slotp + vread[dt]);
;           if (br == 1) {
;             const bool bit = (selmask >> (kb >> 6)) & 1u;
;             if (kb + 31 + 128 <= t0) attn_step<true, false>(kv, kb, t, lane, bit, tabh, q, O, nRs, l);
;             else attn_step<true, true>(kv, kb, t, lane, bit, tabh, q, O, nRs, l);
;           } else {
;             const bool gen = (kb + 31 + 128 > t0) || (kb + 512 <= t0 + 15);
;             if (!gen) attn_step<false, false>(kv, kb, t, lane, true, tabh, q, O, nRw, l);
;             else attn_step<false, true>(kv, kb, t, lane, true, tabh, q, O, nRw, l);
;           }
.Lat_noga_xa0:
	v_exp_f32_e32 v198, v100
	v_exp_f32_e32 v199, v101
	v_exp_f32_e32 v200, v102
	v_exp_f32_e32 v201, v103
	v_exp_f32_e32 v202, v104
	v_exp_f32_e32 v203, v105
	v_exp_f32_e32 v204, v106
	v_exp_f32_e32 v205, v107
	v_exp_f32_e32 v206, v108
	v_exp_f32_e32 v207, v109
	v_exp_f32_e32 v208, v110
	v_exp_f32_e32 v209, v111
	v_exp_f32_e32 v210, v112
	v_exp_f32_e32 v211, v113
	v_exp_f32_e32 v212, v114
	v_exp_f32_e32 v213, v115
	v_cvt_pkrtz_f16_f32 v120, v198, v199
	v_cvt_pkrtz_f16_f32 v121, v200, v201
	v_cvt_pkrtz_f16_f32 v122, v202, v203
	v_cvt_pkrtz_f16_f32 v123, v204, v205
	v_cvt_pkrtz_f16_f32 v124, v206, v207
	v_cvt_pkrtz_f16_f32 v125, v208, v209
	v_cvt_pkrtz_f16_f32 v126, v210, v211
	v_cvt_pkrtz_f16_f32 v127, v212, v213
	s_waitcnt lgkmcnt(0)
	s_mov_b32 s44, s12
	v_mfma_f32_16x16x32_f16 v[100:103], v[96:99], v[8:11], v[128:131]
	s_add_i32 s8, s45, 64
	s_min_i32 s8, s8, s14
	s_mul_i32 s8, s8, s42
	v_mfma_f32_16x16x32_f16 v[104:107], v[88:91], v[8:11], v[128:131]
	s_mov_b32 s9, 0
	s_add_i32 m0, s22, 0x1d880
	v_lshl_add_u64 v[238:239], v[240:241], 0, s[8:9]
	v_mfma_f32_16x16x32_f16 v[108:111], v[96:99], v[16:19], v[132:135]
	global_load_lds_dwordx4 v[238:239], off
	s_add_i32 s45, s45, 32
	s_add_i32 s41, s41, -1
	s_cmp_gt_i32 s45, s39
	v_mfma_f32_16x16x32_f16 v[112:115], v[88:91], v[16:19], v[132:135]
	s_cselect_b32 s11, 2, 0
	s_cmp_le_i32 s45, s43
	s_cselect_b32 s10, 2, 0
	v_mfma_f32_16x16x32_f16 v[100:103], v[92:95], v[12:15], v[100:103]
	s_and_b32 s10, s10, s4
	s_or_b32 s11, s11, s10
	s_lshr_b32 s10, s45, 6
	v_mfma_f32_16x16x32_f16 v[104:107], v[84:87], v[12:15], v[104:107]
	v_bfe_u32 v66, v244, s10, 1
	v_cmp_ne_u32_e32 vcc, 0, v66
	s_cmp_lg_u64 vcc, 0
	s_cselect_b32 s10, 1, 0
	v_mfma_f32_16x16x32_f16 v[108:111], v[92:95], v[20:23], v[108:111]
	s_lshr_b32 s9, s11, 1
	s_or_b32 s10, s10, s9
	s_cmp_le_i32 s45, s15
	v_mfma_f32_16x16x32_f16 v[112:115], v[84:87], v[20:23], v[112:115]
	s_cselect_b32 s10, s10, 0
	s_cmp_ge_i32 s45, s40
	s_cselect_b32 s10, s10, 0
	s_or_b32 s12, s11, s10
	v_mfma_f32_16x16x32_f16 v[60:63], v[80:83], v[120:123], v[60:63]
	v_add_f32_e32 v214, v214, v198
	v_add_f32_e32 v215, v215, v199
	v_mfma_f32_16x16x32_f16 v[56:59], v[76:79], v[120:123], v[56:59]
	v_add_f32_e32 v216, v216, v200
	v_add_f32_e32 v217, v217, v201
	v_mfma_f32_16x16x32_f16 v[52:55], v[72:75], v[120:123], v[52:55]
	v_add_f32_e32 v214, v214, v202
	v_add_f32_e32 v215, v215, v203
	v_mfma_f32_16x16x32_f16 v[48:51], v[68:71], v[120:123], v[48:51]
	v_add_f32_e32 v216, v216, v204
	v_add_f32_e32 v217, v217, v205
	v_mfma_f32_16x16x32_f16 v[44:47], v[80:83], v[124:127], v[44:47]
	v_add_f32_e32 v218, v218, v206
	v_add_f32_e32 v219, v219, v207
	v_mfma_f32_16x16x32_f16 v[40:43], v[76:79], v[124:127], v[40:43]
	v_add_f32_e32 v220, v220, v208
	v_add_f32_e32 v221, v221, v209
	v_mfma_f32_16x16x32_f16 v[36:39], v[72:75], v[124:127], v[36:39]
	v_add_f32_e32 v218, v218, v210
	v_add_f32_e32 v219, v219, v211
	v_mfma_f32_16x16x32_f16 v[32:35], v[68:71], v[124:127], v[32:35]
	v_add_f32_e32 v220, v220, v212
	v_add_f32_e32 v221, v221, v213
	ds_read_b128 v[80:83], v65 offset:4096
	ds_read_b128 v[76:79], v65 offset:5120
	ds_read_b128 v[72:75], v65 offset:6144
	ds_read_b128 v[68:71], v65 offset:7168
	s_cmp_lg_u32 s41, 0
	s_cbranch_scc1 .Lat_xtop1
	s_branch .Lat_xexit
.Lat_xb0:
	s_waitcnt lgkmcnt(0)
	s_mov_b32 s44, s12
	v_mfma_f32_16x16x32_f16 v[100:103], v[96:99], v[8:11], v[128:131]
	s_add_i32 s8, s45, 64
	s_min_i32 s8, s8, s14
	s_mul_i32 s8, s8, s42
	v_mfma_f32_16x16x32_f16 v[104:107], v[88:91], v[8:11], v[128:131]
	s_mov_b32 s9, 0
	s_add_i32 m0, s22, 0x1d880
	v_lshl_add_u64 v[238:239], v[240:241], 0, s[8:9]
	v_mfma_f32_16x16x32_f16 v[108:111], v[96:99], v[16:19], v[132:135]
	global_load_lds_dwordx4 v[238:239], off
	s_add_i32 s45, s45, 32
	s_add_i32 s41, s41, -1
	s_cmp_gt_i32 s45, s39
	v_mfma_f32_16x16x32_f16 v[112:115], v[88:91], v[16:19], v[132:135]
	s_cselect_b32 s11, 2, 0
	s_cmp_le_i32 s45, s43
	s_cselect_b32 s10, 2, 0
	v_mfma_f32_16x16x32_f16 v[100:103], v[92:95], v[12:15], v[100:103]
	s_and_b32 s10, s10, s4
	s_or_b32 s11, s11, s10
	s_lshr_b32 s10, s45, 6
	v_mfma_f32_16x16x32_f16 v[104:107], v[84:87], v[12:15], v[104:107]
	v_bfe_u32 v66, v244, s10, 1
	v_cmp_ne_u32_e32 vcc, 0, v66
	s_cmp_lg_u64 vcc, 0
	s_cselect_b32 s10, 1, 0
	v_mfma_f32_16x16x32_f16 v[108:111], v[92:95], v[20:23], v[108:111]
	s_lshr_b32 s9, s11, 1
	s_or_b32 s10, s10, s9
	s_cmp_le_i32 s45, s15
	v_mfma_f32_16x16x32_f16 v[112:115], v[84:87], v[20:23], v[112:115]
	s_cselect_b32 s10, s10, 0
	s_cmp_ge_i32 s45, s40
	s_cselect_b32 s10, s10, 0
	s_or_b32 s12, s11, s10
	ds_read_b128 v[80:83], v65 offset:4096
	ds_read_b128 v[76:79], v65 offset:5120
	ds_read_b128 v[72:75], v65 offset:6144
	ds_read_b128 v[68:71], v65 offset:7168
	s_cmp_lg_u32 s41, 0
	s_cbranch_scc1 .Lat_xtop1
	s_branch .Lat_xexit

; #define MFMA16(a, b, c) __builtin_amdgcn_mfma_f32_16x16x32_f16((a), (b), (c), 0, 0, 0)
; #define LAS __attribute__((address_space(3)))
; template <bool SEL, bool GEN>
; DI void attn_step(const KF& kv, const int kb, const int t, const int lane, const bool selbit,
;                   const LAS float* tabh, const half8 (&q)[2][2], f32x4 (&O)[2][4], const float (&nR)[2], float (&l)[2]) {
;     ...
;   half8 pf[2];
; #pragma unroll
;   for (int hp = 0; hp < 2; ++hp) {
;     f32x4 p0, p1;
; #pragma unroll
;     for (int j = 0; j < 4; ++j) { p0[j] = __builtin_amdgcn_exp2f(s[hp][0][j]); p1[j] = __builtin_amdgcn_exp2f(s[hp][1][j]); }
;     l[hp] += ((p0[0] + p0[1]) + (p0[2] + p0[3])) + ((p1[0] + p1[1]) + (p1[2] + p1[3]));
;     pf[hp] = pack8(p0, p1);
;   }
; #pragma unroll
;   for (int dt = 0; dt < 4; ++dt)
; #pragma unroll
;     for (int hp = 0; hp < 2; ++hp) O[hp][dt] = MFMA16(kv.v[dt], pf[hp], O[hp][dt]);
; DI void attn_phase(const Params& p, const int layer, const int wid_s) {
;     ...
;         for (int si = 0; si < nsteps; ++si) {
;           asm volatile("s_waitcnt vmcnt(1) lgkmcnt(0)" ::: "memory");
;           __builtin_amdgcn_s_barrier();
;           asm volatile("" ::: "memory");
;           RING_ISSUE(si + 2);
;           const int kb = kb0 + si * 32;
;           if (kb > kmax_w || kb < lo_w) continue;
;           if (br == 1 && kb + 31 + 128 <= t0 && __ballot((selmask >> (kb >> 6)) & 1u) == 0ull) continue;
;           LAS unsigned char* slotp = ring + (si % 3) * 8192;
;           KF kv;
; #pragma unroll
;           for (int kt = 0; kt < 2; ++kt)
; #pragma unroll
;             for (int ks = 0; ks < 2; ++ks) kv.k[kt][ks] = *(const LAS half8*)(slotp + kread[kt][ks]);
; #pragma unroll
;           for (int dt = 0; dt < 4; ++dt) kv.v[dt] = *(const LAS half8*)(slotp + vread[dt]);
;           if (br == 1) {
;             const bool bit = (selmask >> (kb >> 6)) & 1u;
;             if (kb + 31 + 128 <= t0) attn_step<true, false>(kv, kb, t, lane, bit, tabh, q, O, nRs, l);
;             else attn_step<true, true>(kv, kb, t, lane, bit, tabh, q, O, nRs, l);
;           } else {
;             const bool gen = (kb + 31 + 128 > t0) || (kb + 512 <= t0 + 15);
;             if (!gen) attn_step<false, false>(kv, kb, t, lane, true, tabh, q, O, nRw, l);
;             else attn_step<false, true>(kv, kb, t, lane, true, tabh, q, O, nRw, l);
;           }
.Lat_noga_xc0:
	v_exp_f32_e32 v198, v100
	v_exp_f32_e32 v199, v101
	v_exp_f32_e32 v200, v102
	v_exp_f32_e32 v201, v103
	v_exp_f32_e32 v202, v104
	v_exp_f32_e32 v203, v105
	v_exp_f32_e32 v204, v106
	v_exp_f32_e32 v205, v107
	v_exp_f32_e32 v206, v108
	v_exp_f32_e32 v207, v109
	v_exp_f32_e32 v208, v110
	v_exp_f32_e32 v209, v111
	v_exp_f32_e32 v210, v112
	v_exp_f32_e32 v211, v113
	v_exp_f32_e32 v212, v114
	v_exp_f32_e32 v213, v115
	v_cvt_pkrtz_f16_f32 v120, v198, v199
	v_cvt_pkrtz_f16_f32 v121, v200, v201
	v_cvt_pkrtz_f16_f32 v122, v202, v203
	v_cvt_pkrtz_f16_f32 v123, v204, v205
	v_cvt_pkrtz_f16_f32 v124, v206, v207
	v_cvt_pkrtz_f16_f32 v125, v208, v209
	v_cvt_pkrtz_f16_f32 v126, v210, v211
	v_cvt_pkrtz_f16_f32 v127, v212, v213
	s_waitcnt lgkmcnt(0)
	v_mfma_f32_16x16x32_f16 v[60:63], v[80:83], v[120:123], v[60:63]
	v_add_f32_e32 v214, v214, v198
	v_add_f32_e32 v215, v215, v199
	v_add_f32_e32 v216, v216, v200
	v_add_f32_e32 v217, v217, v201
	v_add_f32_e32 v214, v214, v202
	v_mfma_f32_16x16x32_f16 v[56:59], v[76:79], v[120:123], v[56:59]
	v_add_f32_e32 v215, v215, v203
	v_add_f32_e32 v216, v216, v204
	v_add_f32_e32 v217, v217, v205
	v_add_f32_e32 v218, v218, v206
	v_add_f32_e32 v219, v219, v207
	v_mfma_f32_16x16x32_f16 v[52:55], v[72:75], v[120:123], v[52:55]
	v_add_f32_e32 v220, v220, v208
	v_add_f32_e32 v221, v221, v209
	v_add_f32_e32 v218, v218, v210
	v_add_f32_e32 v219, v219, v211
	v_add_f32_e32 v220, v220, v212
	v_add_f32_e32 v221, v221, v213
	v_mfma_f32_16x16x32_f16 v[48:51], v[68:71], v[120:123], v[48:51]
	s_add_i32 s8, s45, 64
	s_min_i32 s8, s8, s14
	s_mul_i32 s8, s8, s42
	s_mov_b32 s9, 0
	s_add_i32 m0, s22, 0x1d880
	v_mfma_f32_16x16x32_f16 v[44:47], v[80:83], v[124:127], v[44:47]
	v_lshl_add_u64 v[238:239], v[240:241], 0, s[8:9]
	global_load_lds_dwordx4 v[238:239], off
	s_add_i32 s45, s45, 32
	s_add_i32 s41, s41, -1
	s_cmp_gt_i32 s45, s39
	v_mfma_f32_16x16x32_f16 v[40:43], v[76:79], v[124:127], v[40:43]
	s_cselect_b32 s11, 2, 0
	s_cmp_le_i32 s45, s43
	s_cselect_b32 s10, 2, 0
	s_and_b32 s10, s10, s4
	s_or_b32 s11, s11, s10
	s_lshr_b32 s10, s45, 6
	v_mfma_f32_16x16x32_f16 v[36:39], v[72:75], v[124:127], v[36:39]
	v_bfe_u32 v66, v244, s10, 1
	v_cmp_ne_u32_e32 vcc, 0, v66
	s_cmp_lg_u64 vcc, 0
	s_cselect_b32 s10, 1, 0
	s_lshr_b32 s9, s11, 1
	v_mfma_f32_16x16x32_f16 v[32:35], v[68:71], v[124:127], v[32:35]
	s_or_b32 s10, s10, s9
	s_cmp_le_i32 s45, s15
	s_cselect_b32 s10, s10, 0
	s_cmp_ge_i32 s45, s40
	s_cselect_b32 s10, s10, 0
	s_or_b32 s12, s11, s10
	s_mov_b32 s44, 0
	s_cmp_lg_u32 s41, 0
	s_cbranch_scc1 .Lat_xtop1
	s_branch .Lat_xexit
.Lat_xd0:
	s_add_i32 s8, s45, 64
	s_min_i32 s8, s8, s14
	s_mul_i32 s8, s8, s42
	s_mov_b32 s9, 0
	s_add_i32 m0, s22, 0x1d880
	v_lshl_add_u64 v[238:239], v[240:241], 0, s[8:9]
	global_load_lds_dwordx4 v[238:239], off
	s_add_i32 s45, s45, 32
	s_add_i32 s41, s41, -1
	s_cmp_gt_i32 s45, s39
	s_cselect_b32 s11, 2, 0
	s_cmp_le_i32 s45, s43
	s_cselect_b32 s10, 2, 0
	s_and_b32 s10, s10, s4
	s_or_b32 s11, s11, s10
	s_lshr_b32 s10, s45, 6
	v_bfe_u32 v66, v244, s10, 1
	v_cmp_ne_u32_e32 vcc, 0, v66
	s_cmp_lg_u64 vcc, 0
	s_cselect_b32 s10, 1, 0
	s_lshr_b32 s9, s11, 1
	s_or_b32 s10, s10, s9
	s_cmp_le_i32 s45, s15
	s_cselect_b32 s10, s10, 0
	s_cmp_ge_i32 s45, s40
	s_cselect_b32 s10, s10, 0
	s_or_b32 s12, s11, s10
	s_cmp_lg_u32 s41, 0
	s_cbranch_scc1 .Lat_xtop1
	s_branch .Lat_xexit

; #define MFMA16(a, b, c) __builtin_amdgcn_mfma_f32_16x16x32_f16((a), (b), (c), 0, 0, 0)
; #define LAS __attribute__((address_space(3)))
; template <bool SEL, bool GEN>
; DI void attn_step(const KF& kv, const int kb, const int t, const int lane, const bool selbit,
;                   const LAS float* tabh, const half8 (&q)[2][2], f32x4 (&O)[2][4], const float (&nR)[2], float (&l)[2]) {
;     ...
;   half8 pf[2];
; #pragma unroll
;   for (int hp = 0; hp < 2; ++hp) {
;     f32x4 p0, p1;
; #pragma unroll
;     for (int j = 0; j < 4; ++j) { p0[j] = __builtin_amdgcn_exp2f(s[hp][0][j]); p1[j] = __builtin_amdgcn_exp2f(s[hp][1][j]); }
;     l[hp] += ((p0[0] + p0[1]) + (p0[2] + p0[3])) + ((p1[0] + p1[1]) + (p1[2] + p1[3]));
;     pf[hp] = pack8(p0, p1);
;   }
; #pragma unroll
;   for (int dt = 0; dt < 4; ++dt)
; #pragma unroll
;     for (int hp = 0; hp < 2; ++hp) O[hp][dt] = MFMA16(kv.v[dt], pf[hp], O[hp][dt]);
; DI void attn_phase(const Params& p, const int layer, const int wid_s) {
;     ...
;         for (int si = 0; si < nsteps; ++si) {
;           asm volatile("s_waitcnt vmcnt(1) lgkmcnt(0)" ::: "memory");
;           __builtin_amdgcn_s_barrier();
;           asm volatile("" ::: "memory");
;           RING_ISSUE(si + 2);
;           const int kb = kb0 + si * 32;
;           if (kb > kmax_w || kb < lo_w) continue;
;           if (br == 1 && kb + 31 + 128 <= t0 && __ballot((selmask >> (kb >> 6)) & 1u) == 0ull) continue;
;           LAS unsigned char* slotp = ring + (si % 3) * 8192;
;           KF kv;
; #pragma unroll
;           for (int kt = 0; kt < 2; ++kt)
; #pragma unroll
;             for (int ks = 0; ks < 2; ++ks) kv.k[kt][ks] = *(const LAS half8*)(slotp + kread[kt][ks]);
; #pragma unroll
;           for (int dt = 0; dt < 4; ++dt) kv.v[dt] = *(const LAS half8*)(slotp + vread[dt]);
;           if (br == 1) {
;             const bool bit = (selmask >> (kb >> 6)) & 1u;
;             if (kb + 31 + 128 <= t0) attn_step<true, false>(kv, kb, t, lane, bit, tabh, q, O, nRs, l);
;             else attn_step<true, true>(kv, kb, t, lane, bit, tabh, q, O, nRs, l);
;           } else {
;             const bool gen = (kb + 31 + 128 > t0) || (kb + 512 <= t0 + 15);
;             if (!gen) attn_step<false, false>(kv, kb, t, lane, true, tabh, q, O, nRw, l);
;             else attn_step<false, true>(kv, kb, t, lane, true, tabh, q, O, nRw, l);
;           }
.Lat_noga_xa1:
	v_exp_f32_e32 v198, v100
	v_exp_f32_e32 v199, v101
	v_exp_f32_e32 v200, v102
	v_exp_f32_e32 v201, v103
	v_exp_f32_e32 v202, v104
	v_exp_f32_e32 v203, v105
	v_exp_f32_e32 v204, v106
	v_exp_f32_e32 v205, v107
	v_exp_f32_e32 v206, v108
	v_exp_f32_e32 v207, v109
	v_exp_f32_e32 v208, v110
	v_exp_f32_e32 v209, v111
	v_exp_f32_e32 v210, v112
	v_exp_f32_e32 v211, v113
	v_exp_f32_e32 v212, v114
	v_exp_f32_e32 v213, v115
	v_cvt_pkrtz_f16_f32 v120, v198, v199
	v_cvt_pkrtz_f16_f32 v121, v200, v201
	v_cvt_pkrtz_f16_f32 v122, v202, v203
	v_cvt_pkrtz_f16_f32 v123, v204, v205
	v_cvt_pkrtz_f16_f32 v124, v206, v207
	v_cvt_pkrtz_f16_f32 v125, v208, v209
	v_cvt_pkrtz_f16_f32 v126, v210, v211
	v_cvt_pkrtz_f16_f32 v127, v212, v213
	s_waitcnt lgkmcnt(0)
	s_mov_b32 s44, s12
	v_mfma_f32_16x16x32_f16 v[100:103], v[96:99], v[8:11], v[128:131]
	s_add_i32 s8, s45, 64
	s_min_i32 s8, s8, s14
	s_mul_i32 s8, s8, s42
	v_mfma_f32_16x16x32_f16 v[104:107], v[88:91], v[8:11], v[128:131]
	s_mov_b32 s9, 0
	s_add_i32 m0, s22, 0x20080
	v_lshl_add_u64 v[238:239], v[240:241], 0, s[8:9]
	v_mfma_f32_16x16x32_f16 v[108:111], v[96:99], v[16:19], v[132:135]
	global_load_lds_dwordx4 v[238:239], off
	s_add_i32 s45, s45, 32
	s_add_i32 s41, s41, -1
	s_cmp_gt_i32 s45, s39
	v_mfma_f32_16x16x32_f16 v[112:115], v[88:91], v[16:19], v[132:135]
	s_cselect_b32 s11, 2, 0
	s_cmp_le_i32 s45, s43
	s_cselect_b32 s10, 2, 0
	v_mfma_f32_16x16x32_f16 v[100:103], v[92:95], v[12:15], v[100:103]
	s_and_b32 s10, s10, s4
	s_or_b32 s11, s11, s10
	s_lshr_b32 s10, s45, 6
	v_mfma_f32_16x16x32_f16 v[104:107], v[84:87], v[12:15], v[104:107]
	v_bfe_u32 v66, v244, s10, 1
	v_cmp_ne_u32_e32 vcc, 0, v66
	s_cmp_lg_u64 vcc, 0
	s_cselect_b32 s10, 1, 0
	v_mfma_f32_16x16x32_f16 v[108:111], v[92:95], v[20:23], v[108:111]
	s_lshr_b32 s9, s11, 1
	s_or_b32 s10, s10, s9
	s_cmp_le_i32 s45, s15
	v_mfma_f32_16x16x32_f16 v[112:115], v[84:87], v[20:23], v[112:115]
	s_cselect_b32 s10, s10, 0
	s_cmp_ge_i32 s45, s40
	s_cselect_b32 s10, s10, 0
	s_or_b32 s12, s11, s10
	v_mfma_f32_16x16x32_f16 v[60:63], v[80:83], v[120:123], v[60:63]
	v_add_f32_e32 v214, v214, v198
	v_add_f32_e32 v215, v215, v199
	v_mfma_f32_16x16x32_f16 v[56:59], v[76:79], v[120:123], v[56:59]
	v_add_f32_e32 v216, v216, v200
	v_add_f32_e32 v217, v217, v201
	v_mfma_f32_16x16x32_f16 v[52:55], v[72:75], v[120:123], v[52:55]
	v_add_f32_e32 v214, v214, v202
	v_add_f32_e32 v215, v215, v203
	v_mfma_f32_16x16x32_f16 v[48:51], v[68:71], v[120:123], v[48:51]
	v_add_f32_e32 v216, v216, v204
	v_add_f32_e32 v217, v217, v205
	v_mfma_f32_16x16x32_f16 v[44:47], v[80:83], v[124:127], v[44:47]
	v_add_f32_e32 v218, v218, v206
	v_add_f32_e32 v219, v219, v207
	v_mfma_f32_16x16x32_f16 v[40:43], v[76:79], v[124:127], v[40:43]
	v_add_f32_e32 v220, v220, v208
	v_add_f32_e32 v221, v221, v209
	v_mfma_f32_16x16x32_f16 v[36:39], v[72:75], v[124:127], v[36:39]
	v_add_f32_e32 v218, v218, v210
	v_add_f32_e32 v219, v219, v211
	v_mfma_f32_16x16x32_f16 v[32:35], v[68:71], v[124:127], v[32:35]
	v_add_f32_e32 v220, v220, v212
	v_add_f32_e32 v221, v221, v213
	ds_read_b128 v[80:83], v65 offset:12288
	ds_read_b128 v[76:79], v65 offset:13312
	ds_read_b128 v[72:75], v65 offset:14336
	ds_read_b128 v[68:71], v65 offset:15360
	s_cmp_lg_u32 s41, 0
	s_cbranch_scc1 .Lat_xtop2
	s_branch .Lat_xexit
.Lat_xb1:
	s_waitcnt lgkmcnt(0)
	s_mov_b32 s44, s12
	v_mfma_f32_16x16x32_f16 v[100:103], v[96:99], v[8:11], v[128:131]
	s_add_i32 s8, s45, 64
	s_min_i32 s8, s8, s14
	s_mul_i32 s8, s8, s42
	v_mfma_f32_16x16x32_f16 v[104:107], v[88:91], v[8:11], v[128:131]
	s_mov_b32 s9, 0
	s_add_i32 m0, s22, 0x20080
	v_lshl_add_u64 v[238:239], v[240:241], 0, s[8:9]
	v_mfma_f32_16x16x32_f16 v[108:111], v[96:99], v[16:19], v[132:135]
	global_load_lds_dwordx4 v[238:239], off
	s_add_i32 s45, s45, 32
	s_add_i32 s41, s41, -1
	s_cmp_gt_i32 s45, s39
	v_mfma_f32_16x16x32_f16 v[112:115], v[88:91], v[16:19], v[132:135]
	s_cselect_b32 s11, 2, 0
	s_cmp_le_i32 s45, s43
	s_cselect_b32 s10, 2, 0
	v_mfma_f32_16x16x32_f16 v[100:103], v[92:95], v[12:15], v[100:103]
	s_and_b32 s10, s10, s4
	s_or_b32 s11, s11, s10
	s_lshr_b32 s10, s45, 6
	v_mfma_f32_16x16x32_f16 v[104:107], v[84:87], v[12:15], v[104:107]
	v_bfe_u32 v66, v244, s10, 1
	v_cmp_ne_u32_e32 vcc, 0, v66
	s_cmp_lg_u64 vcc, 0
	s_cselect_b32 s10, 1, 0
	v_mfma_f32_16x16x32_f16 v[108:111], v[92:95], v[20:23], v[108:111]
	s_lshr_b32 s9, s11, 1
	s_or_b32 s10, s10, s9
	s_cmp_le_i32 s45, s15
	v_mfma_f32_16x16x32_f16 v[112:115], v[84:87], v[20:23], v[112:115]
	s_cselect_b32 s10, s10, 0
	s_cmp_ge_i32 s45, s40
	s_cselect_b32 s10, s10, 0
	s_or_b32 s12, s11, s10
	ds_read_b128 v[80:83], v65 offset:12288
	ds_read_b128 v[76:79], v65 offset:13312
	ds_read_b128 v[72:75], v65 offset:14336
	ds_read_b128 v[68:71], v65 offset:15360
	s_cmp_lg_u32 s41, 0
	s_cbranch_scc1 .Lat_xtop2
	s_branch .Lat_xexit

; #define MFMA16(a, b, c) __builtin_amdgcn_mfma_f32_16x16x32_f16((a), (b), (c), 0, 0, 0)
; #define LAS __attribute__((address_space(3)))
; template <bool SEL, bool GEN>
; DI void attn_step(const KF& kv, const int kb, const int t, const int lane, const bool selbit,
;                   const LAS float* tabh, const half8 (&q)[2][2], f32x4 (&O)[2][4], const float (&nR)[2], float (&l)[2]) {
;     ...
;   half8 pf[2];
; #pragma unroll
;   for (int hp = 0; hp < 2; ++hp) {
;     f32x4 p0, p1;
; #pragma unroll
;     for (int j = 0; j < 4; ++j) { p0[j] = __builtin_amdgcn_exp2f(s[hp][0][j]); p1[j] = __builtin_amdgcn_exp2f(s[hp][1][j]); }
;     l[hp] += ((p0[0] + p0[1]) + (p0[2] + p0[3])) + ((p1[0] + p1[1]) + (p1[2] + p1[3]));
;     pf[hp] = pack8(p0, p1);
;   }
; #pragma unroll
;   for (int dt = 0; dt < 4; ++dt)
; #pragma unroll
;     for (int hp = 0; hp < 2; ++hp) O[hp][dt] = MFMA16(kv.v[dt], pf[hp], O[hp][dt]);
; DI void attn_phase(const Params& p, const int layer, const int wid_s) {
;     ...
;         for (int si = 0; si < nsteps; ++si) {
;           asm volatile("s_waitcnt vmcnt(1) lgkmcnt(0)" ::: "memory");
;           __builtin_amdgcn_s_barrier();
;           asm volatile("" ::: "memory");
;           RING_ISSUE(si + 2);
;           const int kb = kb0 + si * 32;
;           if (kb > kmax_w || kb < lo_w) continue;
;           if (br == 1 && kb + 31 + 128 <= t0 && __ballot((selmask >> (kb >> 6)) & 1u) == 0ull) continue;
;           LAS unsigned char* slotp = ring + (si % 3) * 8192;
;           KF kv;
; #pragma unroll
;           for (int kt = 0; kt < 2; ++kt)
; #pragma unroll
;             for (int ks = 0; ks < 2; ++ks) kv.k[kt][ks] = *(const LAS half8*)(slotp + kread[kt][ks]);
; #pragma unroll
;           for (int dt = 0; dt < 4; ++dt) kv.v[dt] = *(const LAS half8*)(slotp + vread[dt]);
;           if (br == 1) {
;             const bool bit = (selmask >> (kb >> 6)) & 1u;
;             if (kb + 31 + 128 <= t0) attn_step<true, false>(kv, kb, t, lane, bit, tabh, q, O, nRs, l);
;             else attn_step<true, true>(kv, kb, t, lane, bit, tabh, q, O, nRs, l);
;           } else {
;             const bool gen = (kb + 31 + 128 > t0) || (kb + 512 <= t0 + 15);
;             if (!gen) attn_step<false, false>(kv, kb, t, lane, true, tabh, q, O, nRw, l);
;             else attn_step<false, true>(kv, kb, t, lane, true, tabh, q, O, nRw, l);
;           }
.Lat_noga_xc1:
	v_exp_f32_e32 v198, v100
	v_exp_f32_e32 v199, v101
	v_exp_f32_e32 v200, v102
	v_exp_f32_e32 v201, v103
	v_exp_f32_e32 v202, v104
	v_exp_f32_e32 v203, v105
	v_exp_f32_e32 v204, v106
	v_exp_f32_e32 v205, v107
	v_exp_f32_e32 v206, v108
	v_exp_f32_e32 v207, v109
	v_exp_f32_e32 v208, v110
	v_exp_f32_e32 v209, v111
	v_exp_f32_e32 v210, v112
	v_exp_f32_e32 v211, v113
	v_exp_f32_e32 v212, v114
	v_exp_f32_e32 v213, v115
	v_cvt_pkrtz_f16_f32 v120, v198, v199
	v_cvt_pkrtz_f16_f32 v121, v200, v201
	v_cvt_pkrtz_f16_f32 v122, v202, v203
	v_cvt_pkrtz_f16_f32 v123, v204, v205
	v_cvt_pkrtz_f16_f32 v124, v206, v207
	v_cvt_pkrtz_f16_f32 v125, v208, v209
	v_cvt_pkrtz_f16_f32 v126, v210, v211
	v_cvt_pkrtz_f16_f32 v127, v212, v213
	s_waitcnt lgkmcnt(0)
	v_mfma_f32_16x16x32_f16 v[60:63], v[80:83], v[120:123], v[60:63]
	v_add_f32_e32 v214, v214, v198
	v_add_f32_e32 v215, v215, v199
	v_add_f32_e32 v216, v216, v200
	v_add_f32_e32 v217, v217, v201
	v_add_f32_e32 v214, v214, v202
	v_mfma_f32_16x16x32_f16 v[56:59], v[76:79], v[120:123], v[56:59]
	v_add_f32_e32 v215, v215, v203
	v_add_f32_e32 v216, v216, v204
	v_add_f32_e32 v217, v217, v205
	v_add_f32_e32 v218, v218, v206
	v_add_f32_e32 v219, v219, v207
	v_mfma_f32_16x16x32_f16 v[52:55], v[72:75], v[120:123], v[52:55]
	v_add_f32_e32 v220, v220, v208
	v_add_f32_e32 v221, v221, v209
	v_add_f32_e32 v218, v218, v210
	v_add_f32_e32 v219, v219, v211
	v_add_f32_e32 v220, v220, v212
	v_add_f32_e32 v221, v221, v213
	v_mfma_f32_16x16x32_f16 v[48:51], v[68:71], v[120:123], v[48:51]
	s_add_i32 s8, s45, 64
	s_min_i32 s8, s8, s14
	s_mul_i32 s8, s8, s42
	s_mov_b32 s9, 0
	s_add_i32 m0, s22, 0x20080
	v_mfma_f32_16x16x32_f16 v[44:47], v[80:83], v[124:127], v[44:47]
	v_lshl_add_u64 v[238:239], v[240:241], 0, s[8:9]
	global_load_lds_dwordx4 v[238:239], off
	s_add_i32 s45, s45, 32
	s_add_i32 s41, s41, -1
	s_cmp_gt_i32 s45, s39
	v_mfma_f32_16x16x32_f16 v[40:43], v[76:79], v[124:127], v[40:43]
	s_cselect_b32 s11, 2, 0
	s_cmp_le_i32 s45, s43
	s_cselect_b32 s10, 2, 0
	s_and_b32 s10, s10, s4
	s_or_b32 s11, s11, s10
	s_lshr_b32 s10, s45, 6
	v_mfma_f32_16x16x32_f16 v[36:39], v[72:75], v[124:127], v[36:39]
	v_bfe_u32 v66, v244, s10, 1
	v_cmp_ne_u32_e32 vcc, 0, v66
	s_cmp_lg_u64 vcc, 0
	s_cselect_b32 s10, 1, 0
	s_lshr_b32 s9, s11, 1
	v_mfma_f32_16x16x32_f16 v[32:35], v[68:71], v[124:127], v[32:35]
	s_or_b32 s10, s10, s9
	s_cmp_le_i32 s45, s15
	s_cselect_b32 s10, s10, 0
	s_cmp_ge_i32 s45, s40
	s_cselect_b32 s10, s10, 0
	s_or_b32 s12, s11, s10
	s_mov_b32 s44, 0
	s_cmp_lg_u32 s41, 0
	s_cbranch_scc1 .Lat_xtop2
	s_branch .Lat_xexit
.Lat_xd1:
	s_add_i32 s8, s45, 64
	s_min_i32 s8, s8, s14
	s_mul_i32 s8, s8, s42
	s_mov_b32 s9, 0
	s_add_i32 m0, s22, 0x20080
	v_lshl_add_u64 v[238:239], v[240:241], 0, s[8:9]
	global_load_lds_dwordx4 v[238:239], off
	s_add_i32 s45, s45, 32
	s_add_i32 s41, s41, -1
	s_cmp_gt_i32 s45, s39
	s_cselect_b32 s11, 2, 0
	s_cmp_le_i32 s45, s43
	s_cselect_b32 s10, 2, 0
	s_and_b32 s10, s10, s4
	s_or_b32 s11, s11, s10
	s_lshr_b32 s10, s45, 6
	v_bfe_u32 v66, v244, s10, 1
	v_cmp_ne_u32_e32 vcc, 0, v66
	s_cmp_lg_u64 vcc, 0
	s_cselect_b32 s10, 1, 0
	s_lshr_b32 s9, s11, 1
	s_or_b32 s10, s10, s9
	s_cmp_le_i32 s45, s15
	s_cselect_b32 s10, s10, 0
	s_cmp_ge_i32 s45, s40
	s_cselect_b32 s10, s10, 0
	s_or_b32 s12, s11, s10
	s_cmp_lg_u32 s41, 0
	s_cbranch_scc1 .Lat_xtop2
	s_branch .Lat_xexit

; template <bool SEL, bool GEN>
; DI void attn_step(const KF& kv, const int kb, const int t, const int lane, const bool selbit,
;                   const LAS float* tabh, const half8 (&q)[2][2], f32x4 (&O)[2][4], const float (&nR)[2], float (&l)[2]) {
;     ...
;   f32x4 s[2][2];
; #pragma unroll
;   for (int hp = 0; hp < 2; ++hp) {
;     float nm = nR[hp];
;     if (SEL) nm = selbit ? nm : MASKV;
;     const f32x4 c0 = {nm, nm, nm, nm};
; #pragma unroll
;     for (int kt = 0; kt < 2; ++kt) {
;       s[hp][kt] = MFMA16(kv.k[kt][0], q[hp][0], c0);
;       s[hp][kt] = MFMA16(kv.k[kt][1], q[hp][1], s[hp][kt]);
;     }
;   }
;   if (GEN) {
;     const int d0 = t - kb - fq * 4;
; #pragma unroll
;     for (int kt = 0; kt < 2; ++kt)
; #pragma unroll
;       for (int j = 0; j < 4; ++j) {
;         const int dist = d0 - (kt * 16 + j);
;         const bool bad = SEL ? (dist < 0) : ((unsigned)dist >= 512u);
; DI void attn_phase(const Params& p, const int layer, const int wid_s) {
;     ...
;         for (int si = 0; si < nsteps; ++si) {
;           asm volatile("s_waitcnt vmcnt(1) lgkmcnt(0)" ::: "memory");
;           __builtin_amdgcn_s_barrier();
;           asm volatile("" ::: "memory");
;           RING_ISSUE(si + 2);
;           const int kb = kb0 + si * 32;
;           if (kb > kmax_w || kb < lo_w) continue;
;           if (br == 1 && kb + 31 + 128 <= t0 && __ballot((selmask >> (kb >> 6)) & 1u) == 0ull) continue;
;           LAS unsigned char* slotp = ring + (si % 3) * 8192;
;           KF kv;
; #pragma unroll
;           for (int kt = 0; kt < 2; ++kt)
; #pragma unroll
;             for (int ks = 0; ks < 2; ++ks) kv.k[kt][ks] = *(const LAS half8*)(slotp + kread[kt][ks]);
; #pragma unroll
;           for (int dt = 0; dt < 4; ++dt) kv.v[dt] = *(const LAS half8*)(slotp + vread[dt]);
;           if (br == 1) {
;             const bool bit = (selmask >> (kb >> 6)) & 1u;
;             if (kb + 31 + 128 <= t0) attn_step<true, false>(kv, kb, t, lane, bit, tabh, q, O, nRs, l);
;             else attn_step<true, true>(kv, kb, t, lane, bit, tabh, q, O, nRs, l);
;           } else {
;             const bool gen = (kb + 31 + 128 > t0) || (kb + 512 <= t0 + 15);
;             if (!gen) attn_step<false, false>(kv, kb, t, lane, true, tabh, q, O, nRw, l);
;             else attn_step<false, true>(kv, kb, t, lane, true, tabh, q, O, nRw, l);
;           }
.Lat_noga_xa2:
	v_exp_f32_e32 v198, v100
	v_exp_f32_e32 v199, v101
	v_exp_f32_e32 v200, v102
	v_exp_f32_e32 v201, v103
	v_exp_f32_e32 v202, v104
	v_exp_f32_e32 v203, v105
	v_exp_f32_e32 v204, v106
	v_exp_f32_e32 v205, v107
	v_exp_f32_e32 v206, v108
	v_exp_f32_e32 v207, v109
	v_exp_f32_e32 v208, v110
	v_exp_f32_e32 v209, v111
	v_exp_f32_e32 v210, v112
	v_exp_f32_e32 v211, v113
	v_exp_f32_e32 v212, v114
	v_exp_f32_e32 v213, v115
	v_cvt_pkrtz_f16_f32 v120, v198, v199
	v_cvt_pkrtz_f16_f32 v121, v200, v201
	v_cvt_pkrtz_f16_f32 v122, v202, v203
	v_cvt_pkrtz_f16_f32 v123, v204, v205
	v_cvt_pkrtz_f16_f32 v124, v206, v207
	v_cvt_pkrtz_f16_f32 v125, v208, v209
	v_cvt_pkrtz_f16_f32 v126, v210, v211
	v_cvt_pkrtz_f16_f32 v127, v212, v213
	s_waitcnt lgkmcnt(0)
	s_mov_b32 s44, s12
	v_mfma_f32_16x16x32_f16 v[100:103], v[96:99], v[8:11], v[128:131]
	s_add_i32 s8, s45, 64
	s_min_i32 s8, s8, s14
	s_mul_i32 s8, s8, s42
	v_mfma_f32_16x16x32_f16 v[104:107], v[88:91], v[8:11], v[128:131]
	s_mov_b32 s9, 0
	s_add_i32 m0, s22, 0x19880
	v_lshl_add_u64 v[238:239], v[240:241], 0, s[8:9]
	v_mfma_f32_16x16x32_f16 v[108:111], v[96:99], v[16:19], v[132:135]
	global_load_lds_dwordx4 v[238:239], off
	s_add_i32 s45, s45, 32
	s_add_i32 s41, s41, -1
	s_cmp_gt_i32 s45, s39
	v_mfma_f32_16x16x32_f16 v[112:115], v[88:91], v[16:19], v[132:135]
	s_cselect_b32 s11, 2, 0
	s_cmp_le_i32 s45, s43
	s_cselect_b32 s10, 2, 0
	v_mfma_f32_16x16x32_f16 v[100:103], v[92:95], v[12:15], v[100:103]
	s_and_b32 s10, s10, s4
	s_or_b32 s11, s11, s10
	s_lshr_b32 s10, s45, 6
	v_mfma_f32_16x16x32_f16 v[104:107], v[84:87], v[12:15], v[104:107]
	v_bfe_u32 v66, v244, s10, 1
	v_cmp_ne_u32_e32 vcc, 0, v66
	s_cmp_lg_u64 vcc, 0
	s_cselect_b32 s10, 1, 0
	v_mfma_f32_16x16x32_f16 v[108:111], v[92:95], v[20:23], v[108:111]
	s_lshr_b32 s9, s11, 1
	s_or_b32 s10, s10, s9
	s_cmp_le_i32 s45, s15
	v_mfma_f32_16x16x32_f16 v[112:115], v[84:87], v[20:23], v[112:115]
	s_cselect_b32 s10, s10, 0
	s_cmp_ge_i32 s45, s40
	s_cselect_b32 s10, s10, 0
	s_or_b32 s12, s11, s10
	v_mfma_f32_16x16x32_f16 v[60:63], v[80:83], v[120:123], v[60:63]
	v_add_f32_e32 v214, v214, v198
	v_add_f32_e32 v215, v215, v199
	v_mfma_f32_16x16x32_f16 v[56:59], v[76:79], v[120:123], v[56:59]
	v_add_f32_e32 v216, v216, v200
	v_add_f32_e32 v217, v217, v201
	v_mfma_f32_16x16x32_f16 v[52:55], v[72:75], v[120:123], v[52:55]
	v_add_f32_e32 v214, v214, v202
	v_add_f32_e32 v215, v215, v203
	v_mfma_f32_16x16x32_f16 v[48:51], v[68:71], v[120:123], v[48:51]
	v_add_f32_e32 v216, v216, v204
	v_add_f32_e32 v217, v217, v205
	v_mfma_f32_16x16x32_f16 v[44:47], v[80:83], v[124:127], v[44:47]
	v_add_f32_e32 v218, v218, v206
	v_add_f32_e32 v219, v219, v207
	v_mfma_f32_16x16x32_f16 v[40:43], v[76:79], v[124:127], v[40:43]
	v_add_f32_e32 v220, v220, v208
	v_add_f32_e32 v221, v221, v209
	v_mfma_f32_16x16x32_f16 v[36:39], v[72:75], v[124:127], v[36:39]
	v_add_f32_e32 v218, v218, v210
	v_add_f32_e32 v219, v219, v211
	v_mfma_f32_16x16x32_f16 v[32:35], v[68:71], v[124:127], v[32:35]
	v_add_f32_e32 v220, v220, v212
	v_add_f32_e32 v221, v221, v213
	ds_read_b128 v[80:83], v65 offset:20480
	ds_read_b128 v[76:79], v65 offset:21504
	ds_read_b128 v[72:75], v65 offset:22528
	ds_read_b128 v[68:71], v65 offset:23552
	s_cmp_lg_u32 s41, 0
	s_cbranch_scc1 .Lat_xtop3
	s_branch .Lat_xexit
.Lat_xb2:
	s_waitcnt lgkmcnt(0)
	s_mov_b32 s44, s12
	v_mfma_f32_16x16x32_f16 v[100:103], v[96:99], v[8:11], v[128:131]
	s_add_i32 s8, s45, 64
	s_min_i32 s8, s8, s14
	s_mul_i32 s8, s8, s42
	v_mfma_f32_16x16x32_f16 v[104:107], v[88:91], v[8:11], v[128:131]
	s_mov_b32 s9, 0
	s_add_i32 m0, s22, 0x19880
	v_lshl_add_u64 v[238:239], v[240:241], 0, s[8:9]
	v_mfma_f32_16x16x32_f16 v[108:111], v[96:99], v[16:19], v[132:135]
	global_load_lds_dwordx4 v[238:239], off
	s_add_i32 s45, s45, 32
	s_add_i32 s41, s41, -1
	s_cmp_gt_i32 s45, s39
	v_mfma_f32_16x16x32_f16 v[112:115], v[88:91], v[16:19], v[132:135]
	s_cselect_b32 s11, 2, 0
	s_cmp_le_i32 s45, s43
	s_cselect_b32 s10, 2, 0
	v_mfma_f32_16x16x32_f16 v[100:103], v[92:95], v[12:15], v[100:103]
	s_and_b32 s10, s10, s4
	s_or_b32 s11, s11, s10
	s_lshr_b32 s10, s45, 6
	v_mfma_f32_16x16x32_f16 v[104:107], v[84:87], v[12:15], v[104:107]
	v_bfe_u32 v66, v244, s10, 1
	v_cmp_ne_u32_e32 vcc, 0, v66
	s_cmp_lg_u64 vcc, 0
	s_cselect_b32 s10, 1, 0
	v_mfma_f32_16x16x32_f16 v[108:111], v[92:95], v[20:23], v[108:111]
	s_lshr_b32 s9, s11, 1
	s_or_b32 s10, s10, s9
	s_cmp_le_i32 s45, s15
	v_mfma_f32_16x16x32_f16 v[112:115], v[84:87], v[20:23], v[112:115]
	s_cselect_b32 s10, s10, 0
	s_cmp_ge_i32 s45, s40
	s_cselect_b32 s10, s10, 0
	s_or_b32 s12, s11, s10
	ds_read_b128 v[80:83], v65 offset:20480
	ds_read_b128 v[76:79], v65 offset:21504
	ds_read_b128 v[72:75], v65 offset:22528
	ds_read_b128 v[68:71], v65 offset:23552
	s_cmp_lg_u32 s41, 0
	s_cbranch_scc1 .Lat_xtop3
	s_branch .Lat_xexit

; template <bool SEL, bool GEN>
; DI void attn_step(const KF& kv, const int kb, const int t, const int lane, const bool selbit,
;                   const LAS float* tabh, const half8 (&q)[2][2], f32x4 (&O)[2][4], const float (&nR)[2], float (&l)[2]) {
;     ...
;   f32x4 s[2][2];
; #pragma unroll
;   for (int hp = 0; hp < 2; ++hp) {
;     float nm = nR[hp];
;     if (SEL) nm = selbit ? nm : MASKV;
;     const f32x4 c0 = {nm, nm, nm, nm};
; #pragma unroll
;     for (int kt = 0; kt < 2; ++kt) {
;       s[hp][kt] = MFMA16(kv.k[kt][0], q[hp][0], c0);
;       s[hp][kt] = MFMA16(kv.k[kt][1], q[hp][1], s[hp][kt]);
;     }
;   }
;   if (GEN) {
;     const int d0 = t - kb - fq * 4;
; #pragma unroll
;     for (int kt = 0; kt < 2; ++kt)
; #pragma unroll
;       for (int j = 0; j < 4; ++j) {
;         const int dist = d0 - (kt * 16 + j);
;         const bool bad = SEL ? (dist < 0) : ((unsigned)dist >= 512u);
; DI void attn_phase(const Params& p, const int layer, const int wid_s) {
;     ...
;         for (int si = 0; si < nsteps; ++si) {
;           asm volatile("s_waitcnt vmcnt(1) lgkmcnt(0)" ::: "memory");
;           __builtin_amdgcn_s_barrier();
;           asm volatile("" ::: "memory");
;           RING_ISSUE(si + 2);
;           const int kb = kb0 + si * 32;
;           if (kb > kmax_w || kb < lo_w) continue;
;           if (br == 1 && kb + 31 + 128 <= t0 && __ballot((selmask >> (kb >> 6)) & 1u) == 0ull) continue;
;           LAS unsigned char* slotp = ring + (si % 3) * 8192;
;           KF kv;
; #pragma unroll
;           for (int kt = 0; kt < 2; ++kt)
; #pragma unroll
;             for (int ks = 0; ks < 2; ++ks) kv.k[kt][ks] = *(const LAS half8*)(slotp + kread[kt][ks]);
; #pragma unroll
;           for (int dt = 0; dt < 4; ++dt) kv.v[dt] = *(const LAS half8*)(slotp + vread[dt]);
;           if (br == 1) {
;             const bool bit = (selmask >> (kb >> 6)) & 1u;
;             if (kb + 31 + 128 <= t0) attn_step<true, false>(kv, kb, t, lane, bit, tabh, q, O, nRs, l);
;             else attn_step<true, true>(kv, kb, t, lane, bit, tabh, q, O, nRs, l);
;           } else {
;             const bool gen = (kb + 31 + 128 > t0) || (kb + 512 <= t0 + 15);
;             if (!gen) attn_step<false, false>(kv, kb, t, lane, true, tabh, q, O, nRw, l);
;             else attn_step<false, true>(kv, kb, t, lane, true, tabh, q, O, nRw, l);
;           }
.Lat_noga_xc2:
	v_exp_f32_e32 v198, v100
	v_exp_f32_e32 v199, v101
	v_exp_f32_e32 v200, v102
	v_exp_f32_e32 v201, v103
	v_exp_f32_e32 v202, v104
	v_exp_f32_e32 v203, v105
	v_exp_f32_e32 v204, v106
	v_exp_f32_e32 v205, v107
	v_exp_f32_e32 v206, v108
	v_exp_f32_e32 v207, v109
	v_exp_f32_e32 v208, v110
	v_exp_f32_e32 v209, v111
	v_exp_f32_e32 v210, v112
	v_exp_f32_e32 v211, v113
	v_exp_f32_e32 v212, v114
	v_exp_f32_e32 v213, v115
	v_cvt_pkrtz_f16_f32 v120, v198, v199
	v_cvt_pkrtz_f16_f32 v121, v200, v201
	v_cvt_pkrtz_f16_f32 v122, v202, v203
	v_cvt_pkrtz_f16_f32 v123, v204, v205
	v_cvt_pkrtz_f16_f32 v124, v206, v207
	v_cvt_pkrtz_f16_f32 v125, v208, v209
	v_cvt_pkrtz_f16_f32 v126, v210, v211
	v_cvt_pkrtz_f16_f32 v127, v212, v213
	s_waitcnt lgkmcnt(0)
	v_mfma_f32_16x16x32_f16 v[60:63], v[80:83], v[120:123], v[60:63]
	v_add_f32_e32 v214, v214, v198
	v_add_f32_e32 v215, v215, v199
	v_add_f32_e32 v216, v216, v200
	v_add_f32_e32 v217, v217, v201
	v_add_f32_e32 v214, v214, v202
	v_mfma_f32_16x16x32_f16 v[56:59], v[76:79], v[120:123], v[56:59]
	v_add_f32_e32 v215, v215, v203
	v_add_f32_e32 v216, v216, v204
	v_add_f32_e32 v217, v217, v205
	v_add_f32_e32 v218, v218, v206
	v_add_f32_e32 v219, v219, v207
	v_mfma_f32_16x16x32_f16 v[52:55], v[72:75], v[120:123], v[52:55]
	v_add_f32_e32 v220, v220, v208
	v_add_f32_e32 v221, v221, v209
	v_add_f32_e32 v218, v218, v210
	v_add_f32_e32 v219, v219, v211
	v_add_f32_e32 v220, v220, v212
	v_add_f32_e32 v221, v221, v213
	v_mfma_f32_16x16x32_f16 v[48:51], v[68:71], v[120:123], v[48:51]
	s_add_i32 s8, s45, 64
	s_min_i32 s8, s8, s14
	s_mul_i32 s8, s8, s42
	s_mov_b32 s9, 0
	s_add_i32 m0, s22, 0x19880
	v_mfma_f32_16x16x32_f16 v[44:47], v[80:83], v[124:127], v[44:47]
	v_lshl_add_u64 v[238:239], v[240:241], 0, s[8:9]
	global_load_lds_dwordx4 v[238:239], off
	s_add_i32 s45, s45, 32
	s_add_i32 s41, s41, -1
	s_cmp_gt_i32 s45, s39
	v_mfma_f32_16x16x32_f16 v[40:43], v[76:79], v[124:127], v[40:43]
	s_cselect_b32 s11, 2, 0
	s_cmp_le_i32 s45, s43
	s_cselect_b32 s10, 2, 0
	s_and_b32 s10, s10, s4
	s_or_b32 s11, s11, s10
	s_lshr_b32 s10, s45, 6
	v_mfma_f32_16x16x32_f16 v[36:39], v[72:75], v[124:127], v[36:39]
	v_bfe_u32 v66, v244, s10, 1
	v_cmp_ne_u32_e32 vcc, 0, v66
	s_cmp_lg_u64 vcc, 0
	s_cselect_b32 s10, 1, 0
	s_lshr_b32 s9, s11, 1
	v_mfma_f32_16x16x32_f16 v[32:35], v[68:71], v[124:127], v[32:35]
	s_or_b32 s10, s10, s9
	s_cmp_le_i32 s45, s15
	s_cselect_b32 s10, s10, 0
	s_cmp_ge_i32 s45, s40
	s_cselect_b32 s10, s10, 0
	s_or_b32 s12, s11, s10
	s_mov_b32 s44, 0
	s_cmp_lg_u32 s41, 0
	s_cbranch_scc1 .Lat_xtop3
	s_branch .Lat_xexit
.Lat_xd2:
	s_add_i32 s8, s45, 64
	s_min_i32 s8, s8, s14
	s_mul_i32 s8, s8, s42
	s_mov_b32 s9, 0
	s_add_i32 m0, s22, 0x19880
	v_lshl_add_u64 v[238:239], v[240:241], 0, s[8:9]
	global_load_lds_dwordx4 v[238:239], off
	s_add_i32 s45, s45, 32
	s_add_i32 s41, s41, -1
	s_cmp_gt_i32 s45, s39
	s_cselect_b32 s11, 2, 0
	s_cmp_le_i32 s45, s43
	s_cselect_b32 s10, 2, 0
	s_and_b32 s10, s10, s4
	s_or_b32 s11, s11, s10
	s_lshr_b32 s10, s45, 6
	v_bfe_u32 v66, v244, s10, 1
	v_cmp_ne_u32_e32 vcc, 0, v66
	s_cmp_lg_u64 vcc, 0
	s_cselect_b32 s10, 1, 0
	s_lshr_b32 s9, s11, 1
	s_or_b32 s10, s10, s9
	s_cmp_le_i32 s45, s15
	s_cselect_b32 s10, s10, 0
	s_cmp_ge_i32 s45, s40
	s_cselect_b32 s10, s10, 0
	s_or_b32 s12, s11, s10
	s_cmp_lg_u32 s41, 0
	s_cbranch_scc1 .Lat_xtop3
	s_branch .Lat_xexit

; template <bool SEL, bool GEN>
; DI void attn_step(const KF& kv, const int kb, const int t, const int lane, const bool selbit,
;                   const LAS float* tabh, const half8 (&q)[2][2], f32x4 (&O)[2][4], const float (&nR)[2], float (&l)[2]) {
;     ...
;   f32x4 s[2][2];
; #pragma unroll
;   for (int hp = 0; hp < 2; ++hp) {
;     float nm = nR[hp];
;     if (SEL) nm = selbit ? nm : MASKV;
;     const f32x4 c0 = {nm, nm, nm, nm};
; #pragma unroll
;     for (int kt = 0; kt < 2; ++kt) {
;       s[hp][kt] = MFMA16(kv.k[kt][0], q[hp][0], c0);
;       s[hp][kt] = MFMA16(kv.k[kt][1], q[hp][1], s[hp][kt]);
;     }
;   }
;   if (GEN) {
;     const int d0 = t - kb - fq * 4;
; #pragma unroll
;     for (int kt = 0; kt < 2; ++kt)
; #pragma unroll
;       for (int j = 0; j < 4; ++j) {
;         const int dist = d0 - (kt * 16 + j);
;         const bool bad = SEL ? (dist < 0) : ((unsigned)dist >= 512u);
; DI void attn_phase(const Params& p, const int layer, const int wid_s) {
;     ...
;         for (int si = 0; si < nsteps; ++si) {
;           asm volatile("s_waitcnt vmcnt(1) lgkmcnt(0)" ::: "memory");
;           __builtin_amdgcn_s_barrier();
;           asm volatile("" ::: "memory");
;           RING_ISSUE(si + 2);
;           const int kb = kb0 + si * 32;
;           if (kb > kmax_w || kb < lo_w) continue;
;           if (br == 1 && kb + 31 + 128 <= t0 && __ballot((selmask >> (kb >> 6)) & 1u) == 0ull) continue;
;           LAS unsigned char* slotp = ring + (si % 3) * 8192;
;           KF kv;
; #pragma unroll
;           for (int kt = 0; kt < 2; ++kt)
; #pragma unroll
;             for (int ks = 0; ks < 2; ++ks) kv.k[kt][ks] = *(const LAS half8*)(slotp + kread[kt][ks]);
; #pragma unroll
;           for (int dt = 0; dt < 4; ++dt) kv.v[dt] = *(const LAS half8*)(slotp + vread[dt]);
;           if (br == 1) {
;             const bool bit = (selmask >> (kb >> 6)) & 1u;
;             if (kb + 31 + 128 <= t0) attn_step<true, false>(kv, kb, t, lane, bit, tabh, q, O, nRs, l);
;             else attn_step<true, true>(kv, kb, t, lane, bit, tabh, q, O, nRs, l);
;           } else {
;             const bool gen = (kb + 31 + 128 > t0) || (kb + 512 <= t0 + 15);
;             if (!gen) attn_step<false, false>(kv, kb, t, lane, true, tabh, q, O, nRw, l);
;             else attn_step<false, true>(kv, kb, t, lane, true, tabh, q, O, nRw, l);
;           }
.Lat_noga_xa3:
	v_exp_f32_e32 v198, v100
	v_exp_f32_e32 v199, v101
	v_exp_f32_e32 v200, v102
	v_exp_f32_e32 v201, v103
	v_exp_f32_e32 v202, v104
	v_exp_f32_e32 v203, v105
	v_exp_f32_e32 v204, v106
	v_exp_f32_e32 v205, v107
	v_exp_f32_e32 v206, v108
	v_exp_f32_e32 v207, v109
	v_exp_f32_e32 v208, v110
	v_exp_f32_e32 v209, v111
	v_exp_f32_e32 v210, v112
	v_exp_f32_e32 v211, v113
	v_exp_f32_e32 v212, v114
	v_exp_f32_e32 v213, v115
	v_cvt_pkrtz_f16_f32 v120, v198, v199
	v_cvt_pkrtz_f16_f32 v121, v200, v201
	v_cvt_pkrtz_f16_f32 v122, v202, v203
	v_cvt_pkrtz_f16_f32 v123, v204, v205
	v_cvt_pkrtz_f16_f32 v124, v206, v207
	v_cvt_pkrtz_f16_f32 v125, v208, v209
	v_cvt_pkrtz_f16_f32 v126, v210, v211
	v_cvt_pkrtz_f16_f32 v127, v212, v213
	s_waitcnt lgkmcnt(0)
	s_mov_b32 s44, s12
	v_mfma_f32_16x16x32_f16 v[100:103], v[96:99], v[8:11], v[128:131]
	s_add_i32 s8, s45, 64
	s_min_i32 s8, s8, s14
	s_mul_i32 s8, s8, s42
	v_mfma_f32_16x16x32_f16 v[104:107], v[88:91], v[8:11], v[128:131]
	s_mov_b32 s9, 0
	s_add_i32 m0, s22, 0x1b880
	v_lshl_add_u64 v[238:239], v[240:241], 0, s[8:9]
	v_mfma_f32_16x16x32_f16 v[108:111], v[96:99], v[16:19], v[132:135]
	global_load_lds_dwordx4 v[238:239], off
	s_add_i32 s45, s45, 32
	s_add_i32 s41, s41, -1
	s_cmp_gt_i32 s45, s39
	v_mfma_f32_16x16x32_f16 v[112:115], v[88:91], v[16:19], v[132:135]
	s_cselect_b32 s11, 2, 0
	s_cmp_le_i32 s45, s43
	s_cselect_b32 s10, 2, 0
	v_mfma_f32_16x16x32_f16 v[100:103], v[92:95], v[12:15], v[100:103]
	s_and_b32 s10, s10, s4
	s_or_b32 s11, s11, s10
	s_lshr_b32 s10, s45, 6
	v_mfma_f32_16x16x32_f16 v[104:107], v[84:87], v[12:15], v[104:107]
	v_bfe_u32 v66, v244, s10, 1
	v_cmp_ne_u32_e32 vcc, 0, v66
	s_cmp_lg_u64 vcc, 0
	s_cselect_b32 s10, 1, 0
	v_mfma_f32_16x16x32_f16 v[108:111], v[92:95], v[20:23], v[108:111]
	s_lshr_b32 s9, s11, 1
	s_or_b32 s10, s10, s9
	s_cmp_le_i32 s45, s15
	v_mfma_f32_16x16x32_f16 v[112:115], v[84:87], v[20:23], v[112:115]
	s_cselect_b32 s10, s10, 0
	s_cmp_ge_i32 s45, s40
	s_cselect_b32 s10, s10, 0
	s_or_b32 s12, s11, s10
	v_mfma_f32_16x16x32_f16 v[60:63], v[80:83], v[120:123], v[60:63]
	v_add_f32_e32 v214, v214, v198
	v_add_f32_e32 v215, v215, v199
	v_mfma_f32_16x16x32_f16 v[56:59], v[76:79], v[120:123], v[56:59]
	v_add_f32_e32 v216, v216, v200
	v_add_f32_e32 v217, v217, v201
	v_mfma_f32_16x16x32_f16 v[52:55], v[72:75], v[120:123], v[52:55]
	v_add_f32_e32 v214, v214, v202
	v_add_f32_e32 v215, v215, v203
	v_mfma_f32_16x16x32_f16 v[48:51], v[68:71], v[120:123], v[48:51]
	v_add_f32_e32 v216, v216, v204
	v_add_f32_e32 v217, v217, v205
	v_mfma_f32_16x16x32_f16 v[44:47], v[80:83], v[124:127], v[44:47]
	v_add_f32_e32 v218, v218, v206
	v_add_f32_e32 v219, v219, v207
	v_mfma_f32_16x16x32_f16 v[40:43], v[76:79], v[124:127], v[40:43]
	v_add_f32_e32 v220, v220, v208
	v_add_f32_e32 v221, v221, v209
	v_mfma_f32_16x16x32_f16 v[36:39], v[72:75], v[124:127], v[36:39]
	v_add_f32_e32 v218, v218, v210
	v_add_f32_e32 v219, v219, v211
	v_mfma_f32_16x16x32_f16 v[32:35], v[68:71], v[124:127], v[32:35]
	v_add_f32_e32 v220, v220, v212
	v_add_f32_e32 v221, v221, v213
	ds_read_b128 v[80:83], v65 offset:30720
	ds_read_b128 v[76:79], v65 offset:31744
	ds_read_b128 v[72:75], v65 offset:32768
	ds_read_b128 v[68:71], v65 offset:33792
	s_cmp_lg_u32 s41, 0
	s_cbranch_scc1 .Lat_xtop
	s_branch .Lat_xexit
.Lat_xb3:
	s_waitcnt lgkmcnt(0)
	s_mov_b32 s44, s12
	v_mfma_f32_16x16x32_f16 v[100:103], v[96:99], v[8:11], v[128:131]
	s_add_i32 s8, s45, 64
	s_min_i32 s8, s8, s14
	s_mul_i32 s8, s8, s42
	v_mfma_f32_16x16x32_f16 v[104:107], v[88:91], v[8:11], v[128:131]
	s_mov_b32 s9, 0
	s_add_i32 m0, s22, 0x1b880
	v_lshl_add_u64 v[238:239], v[240:241], 0, s[8:9]
	v_mfma_f32_16x16x32_f16 v[108:111], v[96:99], v[16:19], v[132:135]
	global_load_lds_dwordx4 v[238:239], off
	s_add_i32 s45, s45, 32
	s_add_i32 s41, s41, -1
	s_cmp_gt_i32 s45, s39
	v_mfma_f32_16x16x32_f16 v[112:115], v[88:91], v[16:19], v[132:135]
	s_cselect_b32 s11, 2, 0
	s_cmp_le_i32 s45, s43
	s_cselect_b32 s10, 2, 0
	v_mfma_f32_16x16x32_f16 v[100:103], v[92:95], v[12:15], v[100:103]
	s_and_b32 s10, s10, s4
	s_or_b32 s11, s11, s10
	s_lshr_b32 s10, s45, 6
	v_mfma_f32_16x16x32_f16 v[104:107], v[84:87], v[12:15], v[104:107]
	v_bfe_u32 v66, v244, s10, 1
	v_cmp_ne_u32_e32 vcc, 0, v66
	s_cmp_lg_u64 vcc, 0
	s_cselect_b32 s10, 1, 0
	v_mfma_f32_16x16x32_f16 v[108:111], v[92:95], v[20:23], v[108:111]
	s_lshr_b32 s9, s11, 1
	s_or_b32 s10, s10, s9
	s_cmp_le_i32 s45, s15
	v_mfma_f32_16x16x32_f16 v[112:115], v[84:87], v[20:23], v[112:115]
	s_cselect_b32 s10, s10, 0
	s_cmp_ge_i32 s45, s40
	s_cselect_b32 s10, s10, 0
	s_or_b32 s12, s11, s10
	ds_read_b128 v[80:83], v65 offset:30720
	ds_read_b128 v[76:79], v65 offset:31744
	ds_read_b128 v[72:75], v65 offset:32768
	ds_read_b128 v[68:71], v65 offset:33792
	s_cmp_lg_u32 s41, 0
	s_cbranch_scc1 .Lat_xtop
	s_branch .Lat_xexit

; template <bool SEL, bool GEN>
; DI void attn_step(const KF& kv, const int kb, const int t, const int lane, const bool selbit,
;                   const LAS float* tabh, const half8 (&q)[2][2], f32x4 (&O)[2][4], const float (&nR)[2], float (&l)[2]) {
;     ...
;   f32x4 s[2][2];
; #pragma unroll
;   for (int hp = 0; hp < 2; ++hp) {
;     float nm = nR[hp];
;     if (SEL) nm = selbit ? nm : MASKV;
;     const f32x4 c0 = {nm, nm, nm, nm};
; #pragma unroll
;     for (int kt = 0; kt < 2; ++kt) {
;       s[hp][kt] = MFMA16(kv.k[kt][0], q[hp][0], c0);
;       s[hp][kt] = MFMA16(kv.k[kt][1], q[hp][1], s[hp][kt]);
;     }
;   }
;   if (GEN) {
;     const int d0 = t - kb - fq * 4;
; #pragma unroll
;     for (int kt = 0; kt < 2; ++kt)
; #pragma unroll
;       for (int j = 0; j < 4; ++j) {
;         const int dist = d0 - (kt * 16 + j);
;         const bool bad = SEL ? (dist < 0) : ((unsigned)dist >= 512u);
; DI void attn_phase(const Params& p, const int layer, const int wid_s) {
;     ...
;         for (int si = 0; si < nsteps; ++si) {
;           asm volatile("s_waitcnt vmcnt(1) lgkmcnt(0)" ::: "memory");
;           __builtin_amdgcn_s_barrier();
;           asm volatile("" ::: "memory");
;           RING_ISSUE(si + 2);
;           const int kb = kb0 + si * 32;
;           if (kb > kmax_w || kb < lo_w) continue;
;           if (br == 1 && kb + 31 + 128 <= t0 && __ballot((selmask >> (kb >> 6)) & 1u) == 0ull) continue;
;           LAS unsigned char* slotp = ring + (si % 3) * 8192;
;           KF kv;
; #pragma unroll
;           for (int kt = 0; kt < 2; ++kt)
; #pragma unroll
;             for (int ks = 0; ks < 2; ++ks) kv.k[kt][ks] = *(const LAS half8*)(slotp + kread[kt][ks]);
; #pragma unroll
;           for (int dt = 0; dt < 4; ++dt) kv.v[dt] = *(const LAS half8*)(slotp + vread[dt]);
;           if (br == 1) {
;             const bool bit = (selmask >> (kb >> 6)) & 1u;
;             if (kb + 31 + 128 <= t0) attn_step<true, false>(kv, kb, t, lane, bit, tabh, q, O, nRs, l);
;             else attn_step<true, true>(kv, kb, t, lane, bit, tabh, q, O, nRs, l);
;           } else {
;             const bool gen = (kb + 31 + 128 > t0) || (kb + 512 <= t0 + 15);
;             if (!gen) attn_step<false, false>(kv, kb, t, lane, true, tabh, q, O, nRw, l);
;             else attn_step<false, true>(kv, kb, t, lane, true, tabh, q, O, nRw, l);
;           }
.Lat_noga_xc3:
	v_exp_f32_e32 v198, v100
	v_exp_f32_e32 v199, v101
	v_exp_f32_e32 v200, v102
	v_exp_f32_e32 v201, v103
	v_exp_f32_e32 v202, v104
	v_exp_f32_e32 v203, v105
	v_exp_f32_e32 v204, v106
	v_exp_f32_e32 v205, v107
	v_exp_f32_e32 v206, v108
	v_exp_f32_e32 v207, v109
	v_exp_f32_e32 v208, v110
	v_exp_f32_e32 v209, v111
	v_exp_f32_e32 v210, v112
	v_exp_f32_e32 v211, v113
	v_exp_f32_e32 v212, v114
	v_exp_f32_e32 v213, v115
	v_cvt_pkrtz_f16_f32 v120, v198, v199
	v_cvt_pkrtz_f16_f32 v121, v200, v201
	v_cvt_pkrtz_f16_f32 v122, v202, v203
	v_cvt_pkrtz_f16_f32 v123, v204, v205
	v_cvt_pkrtz_f16_f32 v124, v206, v207
	v_cvt_pkrtz_f16_f32 v125, v208, v209
	v_cvt_pkrtz_f16_f32 v126, v210, v211
	v_cvt_pkrtz_f16_f32 v127, v212, v213
	s_waitcnt lgkmcnt(0)
	v_mfma_f32_16x16x32_f16 v[60:63], v[80:83], v[120:123], v[60:63]
	v_add_f32_e32 v214, v214, v198
	v_add_f32_e32 v215, v215, v199
	v_add_f32_e32 v216, v216, v200
	v_add_f32_e32 v217, v217, v201
	v_add_f32_e32 v214, v214, v202
	v_mfma_f32_16x16x32_f16 v[56:59], v[76:79], v[120:123], v[56:59]
	v_add_f32_e32 v215, v215, v203
	v_add_f32_e32 v216, v216, v204
	v_add_f32_e32 v217, v217, v205
	v_add_f32_e32 v218, v218, v206
	v_add_f32_e32 v219, v219, v207
	v_mfma_f32_16x16x32_f16 v[52:55], v[72:75], v[120:123], v[52:55]
	v_add_f32_e32 v220, v220, v208
	v_add_f32_e32 v221, v221, v209
	v_add_f32_e32 v218, v218, v210
	v_add_f32_e32 v219, v219, v211
	v_add_f32_e32 v220, v220, v212
	v_add_f32_e32 v221, v221, v213
	v_mfma_f32_16x16x32_f16 v[48:51], v[68:71], v[120:123], v[48:51]
	s_add_i32 s8, s45, 64
	s_min_i32 s8, s8, s14
	s_mul_i32 s8, s8, s42
	s_mov_b32 s9, 0
	s_add_i32 m0, s22, 0x1b880
	v_mfma_f32_16x16x32_f16 v[44:47], v[80:83], v[124:127], v[44:47]
	v_lshl_add_u64 v[238:239], v[240:241], 0, s[8:9]
	global_load_lds_dwordx4 v[238:239], off
	s_add_i32 s45, s45, 32
	s_add_i32 s41, s41, -1
	s_cmp_gt_i32 s45, s39
	v_mfma_f32_16x16x32_f16 v[40:43], v[76:79], v[124:127], v[40:43]
	s_cselect_b32 s11, 2, 0
	s_cmp_le_i32 s45, s43
	s_cselect_b32 s10, 2, 0
	s_and_b32 s10, s10, s4
	s_or_b32 s11, s11, s10
	s_lshr_b32 s10, s45, 6
	v_mfma_f32_16x16x32_f16 v[36:39], v[72:75], v[124:127], v[36:39]
	v_bfe_u32 v66, v244, s10, 1
	v_cmp_ne_u32_e32 vcc, 0, v66
	s_cmp_lg_u64 vcc, 0
	s_cselect_b32 s10, 1, 0
	s_lshr_b32 s9, s11, 1
	v_mfma_f32_16x16x32_f16 v[32:35], v[68:71], v[124:127], v[32:35]
	s_or_b32 s10, s10, s9
	s_cmp_le_i32 s45, s15
	s_cselect_b32 s10, s10, 0
	s_cmp_ge_i32 s45, s40
	s_cselect_b32 s10, s10, 0
	s_or_b32 s12, s11, s10
	s_mov_b32 s44, 0
	s_cmp_lg_u32 s41, 0
	s_cbranch_scc1 .Lat_xtop
	s_branch .Lat_xexit
.Lat_xd3:
	s_add_i32 s8, s45, 64
	s_min_i32 s8, s8, s14
	s_mul_i32 s8, s8, s42
	s_mov_b32 s9, 0
	s_add_i32 m0, s22, 0x1b880
	v_lshl_add_u64 v[238:239], v[240:241], 0, s[8:9]
	global_load_lds_dwordx4 v[238:239], off
	s_add_i32 s45, s45, 32
	s_add_i32 s41, s41, -1
	s_cmp_gt_i32 s45, s39
	s_cselect_b32 s11, 2, 0
	s_cmp_le_i32 s45, s43
	s_cselect_b32 s10, 2, 0
	s_and_b32 s10, s10, s4
	s_or_b32 s11, s11, s10
	s_lshr_b32 s10, s45, 6
	v_bfe_u32 v66, v244, s10, 1
	v_cmp_ne_u32_e32 vcc, 0, v66
	s_cmp_lg_u64 vcc, 0
	s_cselect_b32 s10, 1, 0
	s_lshr_b32 s9, s11, 1
	s_or_b32 s10, s10, s9
	s_cmp_le_i32 s45, s15
	s_cselect_b32 s10, s10, 0
	s_cmp_ge_i32 s45, s40
	s_cselect_b32 s10, s10, 0
	s_or_b32 s12, s11, s10
	s_cmp_lg_u32 s41, 0
	s_cbranch_scc1 .Lat_xtop
	s_branch .Lat_xexit

; template <bool SEL, bool GEN>
; DI void attn_step(const KF& kv, const int kb, const int t, const int lane, const bool selbit,
;                   const LAS float* tabh, const half8 (&q)[2][2], f32x4 (&O)[2][4], const float (&nR)[2], float (&l)[2]) {
;     ...
;   f32x4 s[2][2];
; #pragma unroll
;   for (int hp = 0; hp < 2; ++hp) {
;     float nm = nR[hp];
;     if (SEL) nm = selbit ? nm : MASKV;
;     const f32x4 c0 = {nm, nm, nm, nm};
; #pragma unroll
;     for (int kt = 0; kt < 2; ++kt) {
;       s[hp][kt] = MFMA16(kv.k[kt][0], q[hp][0], c0);
;       s[hp][kt] = MFMA16(kv.k[kt][1], q[hp][1], s[hp][kt]);
;     }
;   }
;   if (GEN) {
;     const int d0 = t - kb - fq * 4;
; #pragma unroll
;     for (int kt = 0; kt < 2; ++kt)
; #pragma unroll
;       for (int j = 0; j < 4; ++j) {
;         const int dist = d0 - (kt * 16 + j);
;         const bool bad = SEL ? (dist < 0) : ((unsigned)dist >= 512u);
; DI void attn_phase(const Params& p, const int layer, const int wid_s) {
;     ...
;         for (int si = 0; si < nsteps; ++si) {
;           asm volatile("s_waitcnt vmcnt(1) lgkmcnt(0)" ::: "memory");
;           __builtin_amdgcn_s_barrier();
;           asm volatile("" ::: "memory");
;           RING_ISSUE(si + 2);
;           const int kb = kb0 + si * 32;
;           if (kb > kmax_w || kb < lo_w) continue;
;           if (br == 1 && kb + 31 + 128 <= t0 && __ballot((selmask >> (kb >> 6)) & 1u) == 0ull) continue;
;           LAS unsigned char* slotp = ring + (si % 3) * 8192;
;           KF kv;
; #pragma unroll
;           for (int kt = 0; kt < 2; ++kt)
; #pragma unroll
;             for (int ks = 0; ks < 2; ++ks) kv.k[kt][ks] = *(const LAS half8*)(slotp + kread[kt][ks]);
; #pragma unroll
;           for (int dt = 0; dt < 4; ++dt) kv.v[dt] = *(const LAS half8*)(slotp + vread[dt]);
;           if (br == 1) {
;             const bool bit = (selmask >> (kb >> 6)) & 1u;
;             if (kb + 31 + 128 <= t0) attn_step<true, false>(kv, kb, t, lane, bit, tabh, q, O, nRs, l);
;             else attn_step<true, true>(kv, kb, t, lane, bit, tabh, q, O, nRs, l);
;           } else {
;             const bool gen = (kb + 31 + 128 > t0) || (kb + 512 <= t0 + 15);
;             if (!gen) attn_step<false, false>(kv, kb, t, lane, true, tabh, q, O, nRw, l);
;             else attn_step<false, true>(kv, kb, t, lane, true, tabh, q, O, nRw, l);
;           }
.Lat_cok_y0:
	s_bitcmp1_b32 s44, 0
	s_cbranch_scc0 .Lat_yb0
	s_waitcnt lgkmcnt(4)
	v_mfma_f32_16x16x32_f16 v[60:63], v[80:83], v[120:123], v[60:63]
	v_add_f32_e32 v214, v214, v198
	v_add_f32_e32 v215, v215, v199
	v_mfma_f32_16x16x32_f16 v[56:59], v[76:79], v[120:123], v[56:59]
	v_add_f32_e32 v216, v216, v200
	v_add_f32_e32 v217, v217, v201
	v_add_f32_e32 v214, v214, v202
	v_mfma_f32_16x16x32_f16 v[52:55], v[72:75], v[120:123], v[52:55]
	v_add_f32_e32 v215, v215, v203
	v_add_f32_e32 v216, v216, v204
	v_add_f32_e32 v217, v217, v205
	v_mfma_f32_16x16x32_f16 v[48:51], v[68:71], v[120:123], v[48:51]
	v_add_f32_e32 v218, v218, v206
	v_add_f32_e32 v219, v219, v207
	v_add_f32_e32 v220, v220, v208
	v_mfma_f32_16x16x32_f16 v[44:47], v[80:83], v[124:127], v[44:47]
	v_add_f32_e32 v221, v221, v209
	v_add_f32_e32 v218, v218, v210
	v_add_f32_e32 v219, v219, v211
	v_mfma_f32_16x16x32_f16 v[40:43], v[76:79], v[124:127], v[40:43]
	v_add_f32_e32 v220, v220, v212
	v_add_f32_e32 v221, v221, v213
	s_add_i32 s8, s45, 64
	v_mfma_f32_16x16x32_f16 v[36:39], v[72:75], v[124:127], v[36:39]
	s_min_i32 s8, s8, s14
	s_mul_i32 s8, s8, s42
	s_mov_b32 s9, 0
	v_mfma_f32_16x16x32_f16 v[32:35], v[68:71], v[124:127], v[32:35]
	s_add_i32 m0, s22, 0x1d880
	v_lshl_add_u64 v[238:239], v[240:241], 0, s[8:9]
	global_load_lds_dwordx4 v[238:239], off
	s_waitcnt lgkmcnt(0)
	s_mov_b32 s44, s12
	v_mfma_f32_16x16x32_f16 v[100:103], v[96:99], v[8:11], v[128:131]
	s_add_i32 s45, s45, 32
	s_add_i32 s41, s41, -1
	v_mfma_f32_16x16x32_f16 v[104:107], v[88:91], v[8:11], v[128:131]
	s_cmp_gt_i32 s45, s39
	s_cselect_b32 s11, 2, 0
	s_cmp_le_i32 s45, s43
	v_mfma_f32_16x16x32_f16 v[108:111], v[96:99], v[16:19], v[132:135]
	s_cselect_b32 s10, 2, 0
	s_and_b32 s10, s10, s4
	v_mfma_f32_16x16x32_f16 v[112:115], v[88:91], v[16:19], v[132:135]
	s_or_b32 s11, s11, s10
	s_lshr_b32 s10, s45, 6
	v_bfe_u32 v66, v244, s10, 1
	v_mfma_f32_16x16x32_f16 v[100:103], v[92:95], v[12:15], v[100:103]
	v_cmp_ne_u32_e32 vcc, 0, v66
	s_cmp_lg_u64 vcc, 0
	v_mfma_f32_16x16x32_f16 v[104:107], v[84:87], v[12:15], v[104:107]
	s_cselect_b32 s10, 1, 0
	s_lshr_b32 s9, s11, 1
	s_or_b32 s10, s10, s9
	v_mfma_f32_16x16x32_f16 v[108:111], v[92:95], v[20:23], v[108:111]
	s_cmp_le_i32 s45, s15
	s_cselect_b32 s10, s10, 0
	v_mfma_f32_16x16x32_f16 v[112:115], v[84:87], v[20:23], v[112:115]
	s_cmp_ge_i32 s45, s40
	s_cselect_b32 s10, s10, 0
	s_or_b32 s12, s11, s10
	ds_read_b128 v[80:83], v65 offset:4096
	ds_read_b128 v[76:79], v65 offset:5120
	ds_read_b128 v[72:75], v65 offset:6144
	ds_read_b128 v[68:71], v65 offset:7168
	s_bitcmp1_b32 s44, 1
	s_cbranch_scc0 .Lat_noga_ya0
	v_add_f32_e32 v100, v100, v222
	v_add_f32_e32 v101, v101, v223
	v_add_f32_e32 v102, v102, v224
	v_add_f32_e32 v103, v103, v225
	v_add_f32_e32 v104, v104, v226
	v_add_f32_e32 v105, v105, v227
	v_add_f32_e32 v106, v106, v228
	v_add_f32_e32 v107, v107, v229
	v_add_f32_e32 v108, v108, v230
	v_add_f32_e32 v109, v109, v231
	v_add_f32_e32 v110, v110, v232
	v_add_f32_e32 v111, v111, v233
	v_add_f32_e32 v112, v112, v234
	v_add_f32_e32 v113, v113, v235
	v_add_f32_e32 v114, v114, v236
	v_add_f32_e32 v115, v115, v237

; template <bool SEL, bool GEN>
; DI void attn_step(const KF& kv, const int kb, const int t, const int lane, const bool selbit,
;                   const LAS float* tabh, const half8 (&q)[2][2], f32x4 (&O)[2][4], const float (&nR)[2], float (&l)[2]) {
;     ...
;   f32x4 s[2][2];
; #pragma unroll
;   for (int hp = 0; hp < 2; ++hp) {
;     float nm = nR[hp];
;     if (SEL) nm = selbit ? nm : MASKV;
;     const f32x4 c0 = {nm, nm, nm, nm};
; #pragma unroll
;     for (int kt = 0; kt < 2; ++kt) {
;       s[hp][kt] = MFMA16(kv.k[kt][0], q[hp][0], c0);
;       s[hp][kt] = MFMA16(kv.k[kt][1], q[hp][1], s[hp][kt]);
;     }
;   }
;   if (GEN) {
;     const int d0 = t - kb - fq * 4;
; #pragma unroll
;     for (int kt = 0; kt < 2; ++kt)
; #pragma unroll
;       for (int j = 0; j < 4; ++j) {
;         const int dist = d0 - (kt * 16 + j);
;         const bool bad = SEL ? (dist < 0) : ((unsigned)dist >= 512u);
; DI void attn_phase(const Params& p, const int layer, const int wid_s) {
;     ...
;         for (int si = 0; si < nsteps; ++si) {
;           asm volatile("s_waitcnt vmcnt(1) lgkmcnt(0)" ::: "memory");
;           __builtin_amdgcn_s_barrier();
;           asm volatile("" ::: "memory");
;           RING_ISSUE(si + 2);
;           const int kb = kb0 + si * 32;
;           if (kb > kmax_w || kb < lo_w) continue;
;           if (br == 1 && kb + 31 + 128 <= t0 && __ballot((selmask >> (kb >> 6)) & 1u) == 0ull) continue;
;           LAS unsigned char* slotp = ring + (si % 3) * 8192;
;           KF kv;
; #pragma unroll
;           for (int kt = 0; kt < 2; ++kt)
; #pragma unroll
;             for (int ks = 0; ks < 2; ++ks) kv.k[kt][ks] = *(const LAS half8*)(slotp + kread[kt][ks]);
; #pragma unroll
;           for (int dt = 0; dt < 4; ++dt) kv.v[dt] = *(const LAS half8*)(slotp + vread[dt]);
;           if (br == 1) {
;             const bool bit = (selmask >> (kb >> 6)) & 1u;
;             if (kb + 31 + 128 <= t0) attn_step<true, false>(kv, kb, t, lane, bit, tabh, q, O, nRs, l);
;             else attn_step<true, true>(kv, kb, t, lane, bit, tabh, q, O, nRs, l);
;           } else {
;             const bool gen = (kb + 31 + 128 > t0) || (kb + 512 <= t0 + 15);
;             if (!gen) attn_step<false, false>(kv, kb, t, lane, true, tabh, q, O, nRw, l);
;             else attn_step<false, true>(kv, kb, t, lane, true, tabh, q, O, nRw, l);
;           }
.Lat_yb0:
	s_waitcnt lgkmcnt(0)
	s_mov_b32 s44, s12
	v_mfma_f32_16x16x32_f16 v[100:103], v[96:99], v[8:11], v[128:131]
	s_add_i32 s8, s45, 64
	s_min_i32 s8, s8, s14
	s_mul_i32 s8, s8, s42
	v_mfma_f32_16x16x32_f16 v[104:107], v[88:91], v[8:11], v[128:131]
	s_mov_b32 s9, 0
	s_add_i32 m0, s22, 0x1d880
	v_lshl_add_u64 v[238:239], v[240:241], 0, s[8:9]
	v_mfma_f32_16x16x32_f16 v[108:111], v[96:99], v[16:19], v[132:135]
	global_load_lds_dwordx4 v[238:239], off
	s_add_i32 s45, s45, 32
	s_add_i32 s41, s41, -1
	s_cmp_gt_i32 s45, s39
	v_mfma_f32_16x16x32_f16 v[112:115], v[88:91], v[16:19], v[132:135]
	s_cselect_b32 s11, 2, 0
	s_cmp_le_i32 s45, s43
	s_cselect_b32 s10, 2, 0
	v_mfma_f32_16x16x32_f16 v[100:103], v[92:95], v[12:15], v[100:103]
	s_and_b32 s10, s10, s4
	s_or_b32 s11, s11, s10
	s_lshr_b32 s10, s45, 6
	v_mfma_f32_16x16x32_f16 v[104:107], v[84:87], v[12:15], v[104:107]
	v_bfe_u32 v66, v244, s10, 1
	v_cmp_ne_u32_e32 vcc, 0, v66
	s_cmp_lg_u64 vcc, 0
	s_cselect_b32 s10, 1, 0
	v_mfma_f32_16x16x32_f16 v[108:111], v[92:95], v[20:23], v[108:111]
	s_lshr_b32 s9, s11, 1
	s_or_b32 s10, s10, s9
	s_cmp_le_i32 s45, s15
	v_mfma_f32_16x16x32_f16 v[112:115], v[84:87], v[20:23], v[112:115]
	s_cselect_b32 s10, s10, 0
	s_cmp_ge_i32 s45, s40
	s_cselect_b32 s10, s10, 0
	s_or_b32 s12, s11, s10
	ds_read_b128 v[80:83], v65 offset:4096
	ds_read_b128 v[76:79], v65 offset:5120
	ds_read_b128 v[72:75], v65 offset:6144
	ds_read_b128 v[68:71], v65 offset:7168
	s_bitcmp1_b32 s44, 1
	s_cbranch_scc0 .Lat_noga_yb0
	v_add_f32_e32 v100, v100, v222
	v_add_f32_e32 v101, v101, v223
	v_add_f32_e32 v102, v102, v224
	v_add_f32_e32 v103, v103, v225
	v_add_f32_e32 v104, v104, v226
	v_add_f32_e32 v105, v105, v227
	v_add_f32_e32 v106, v106, v228
	v_add_f32_e32 v107, v107, v229
	v_add_f32_e32 v108, v108, v230
	v_add_f32_e32 v109, v109, v231
	v_add_f32_e32 v110, v110, v232
	v_add_f32_e32 v111, v111, v233
	v_add_f32_e32 v112, v112, v234
	v_add_f32_e32 v113, v113, v235
	v_add_f32_e32 v114, v114, v236
	v_add_f32_e32 v115, v115, v237

; template <bool SEL, bool GEN>
; DI void attn_step(const KF& kv, const int kb, const int t, const int lane, const bool selbit,
;                   const LAS float* tabh, const half8 (&q)[2][2], f32x4 (&O)[2][4], const float (&nR)[2], float (&l)[2]) {
;     ...
;   f32x4 s[2][2];
; #pragma unroll
;   for (int hp = 0; hp < 2; ++hp) {
;     float nm = nR[hp];
;     if (SEL) nm = selbit ? nm : MASKV;
;     const f32x4 c0 = {nm, nm, nm, nm};
; #pragma unroll
;     for (int kt = 0; kt < 2; ++kt) {
;       s[hp][kt] = MFMA16(kv.k[kt][0], q[hp][0], c0);
;       s[hp][kt] = MFMA16(kv.k[kt][1], q[hp][1], s[hp][kt]);
;     }
;   }
;   if (GEN) {
;     const int d0 = t - kb - fq * 4;
; #pragma unroll
;     for (int kt = 0; kt < 2; ++kt)
; #pragma unroll
;       for (int j = 0; j < 4; ++j) {
;         const int dist = d0 - (kt * 16 + j);
;         const bool bad = SEL ? (dist < 0) : ((unsigned)dist >= 512u);
; DI void attn_phase(const Params& p, const int layer, const int wid_s) {
;     ...
;         for (int si = 0; si < nsteps; ++si) {
;           asm volatile("s_waitcnt vmcnt(1) lgkmcnt(0)" ::: "memory");
;           __builtin_amdgcn_s_barrier();
;           asm volatile("" ::: "memory");
;           RING_ISSUE(si + 2);
;           const int kb = kb0 + si * 32;
;           if (kb > kmax_w || kb < lo_w) continue;
;           if (br == 1 && kb + 31 + 128 <= t0 && __ballot((selmask >> (kb >> 6)) & 1u) == 0ull) continue;
;           LAS unsigned char* slotp = ring + (si % 3) * 8192;
;           KF kv;
; #pragma unroll
;           for (int kt = 0; kt < 2; ++kt)
; #pragma unroll
;             for (int ks = 0; ks < 2; ++ks) kv.k[kt][ks] = *(const LAS half8*)(slotp + kread[kt][ks]);
; #pragma unroll
;           for (int dt = 0; dt < 4; ++dt) kv.v[dt] = *(const LAS half8*)(slotp + vread[dt]);
;           if (br == 1) {
;             const bool bit = (selmask >> (kb >> 6)) & 1u;
;             if (kb + 31 + 128 <= t0) attn_step<true, false>(kv, kb, t, lane, bit, tabh, q, O, nRs, l);
;             else attn_step<true, true>(kv, kb, t, lane, bit, tabh, q, O, nRs, l);
;           } else {
;             const bool gen = (kb + 31 + 128 > t0) || (kb + 512 <= t0 + 15);
;             if (!gen) attn_step<false, false>(kv, kb, t, lane, true, tabh, q, O, nRw, l);
;             else attn_step<false, true>(kv, kb, t, lane, true, tabh, q, O, nRw, l);
;           }
.Lat_yskip0:
	s_bitcmp1_b32 s44, 0
	s_cbranch_scc0 .Lat_yd0
	s_waitcnt lgkmcnt(0)
	v_mfma_f32_16x16x32_f16 v[60:63], v[80:83], v[120:123], v[60:63]
	v_add_f32_e32 v214, v214, v198
	v_add_f32_e32 v215, v215, v199
	v_add_f32_e32 v216, v216, v200
	v_add_f32_e32 v217, v217, v201
	v_add_f32_e32 v214, v214, v202
	v_mfma_f32_16x16x32_f16 v[56:59], v[76:79], v[120:123], v[56:59]
	v_add_f32_e32 v215, v215, v203
	v_add_f32_e32 v216, v216, v204
	v_add_f32_e32 v217, v217, v205
	v_add_f32_e32 v218, v218, v206
	v_add_f32_e32 v219, v219, v207
	v_mfma_f32_16x16x32_f16 v[52:55], v[72:75], v[120:123], v[52:55]
	v_add_f32_e32 v220, v220, v208
	v_add_f32_e32 v221, v221, v209
	v_add_f32_e32 v218, v218, v210
	v_add_f32_e32 v219, v219, v211
	v_add_f32_e32 v220, v220, v212
	v_add_f32_e32 v221, v221, v213
	v_mfma_f32_16x16x32_f16 v[48:51], v[68:71], v[120:123], v[48:51]
	s_add_i32 s8, s45, 64
	s_min_i32 s8, s8, s14
	s_mul_i32 s8, s8, s42
	s_mov_b32 s9, 0
	s_add_i32 m0, s22, 0x1d880
	v_mfma_f32_16x16x32_f16 v[44:47], v[80:83], v[124:127], v[44:47]
	v_lshl_add_u64 v[238:239], v[240:241], 0, s[8:9]
	global_load_lds_dwordx4 v[238:239], off
	s_add_i32 s45, s45, 32
	s_add_i32 s41, s41, -1
	s_cmp_gt_i32 s45, s39
	v_mfma_f32_16x16x32_f16 v[40:43], v[76:79], v[124:127], v[40:43]
	s_cselect_b32 s11, 2, 0
	s_cmp_le_i32 s45, s43
	s_cselect_b32 s10, 2, 0
	s_and_b32 s10, s10, s4
	s_or_b32 s11, s11, s10
	s_lshr_b32 s10, s45, 6
	v_mfma_f32_16x16x32_f16 v[36:39], v[72:75], v[124:127], v[36:39]
	v_bfe_u32 v66, v244, s10, 1
	v_cmp_ne_u32_e32 vcc, 0, v66
	s_cmp_lg_u64 vcc, 0
	s_cselect_b32 s10, 1, 0
	s_lshr_b32 s9, s11, 1
	v_mfma_f32_16x16x32_f16 v[32:35], v[68:71], v[124:127], v[32:35]
	s_or_b32 s10, s10, s9
	s_cmp_le_i32 s45, s15
	s_cselect_b32 s10, s10, 0
	s_cmp_ge_i32 s45, s40
	s_cselect_b32 s10, s10, 0
	s_or_b32 s12, s11, s10
	s_mov_b32 s44, 0
	s_cmp_lg_u32 s41, 0
	s_cbranch_scc1 .Lat_ytop1
	s_branch .Lat_yexit

; template <bool SEL, bool GEN>
; DI void attn_step(const KF& kv, const int kb, const int t, const int lane, const bool selbit,
;                   const LAS float* tabh, const half8 (&q)[2][2], f32x4 (&O)[2][4], const float (&nR)[2], float (&l)[2]) {
;     ...
;   f32x4 s[2][2];
; #pragma unroll
;   for (int hp = 0; hp < 2; ++hp) {
;     float nm = nR[hp];
;     if (SEL) nm = selbit ? nm : MASKV;
;     const f32x4 c0 = {nm, nm, nm, nm};
; #pragma unroll
;     for (int kt = 0; kt < 2; ++kt) {
;       s[hp][kt] = MFMA16(kv.k[kt][0], q[hp][0], c0);
;       s[hp][kt] = MFMA16(kv.k[kt][1], q[hp][1], s[hp][kt]);
;     }
;   }
;   if (GEN) {
;     const int d0 = t - kb - fq * 4;
; #pragma unroll
;     for (int kt = 0; kt < 2; ++kt)
; #pragma unroll
;       for (int j = 0; j < 4; ++j) {
;         const int dist = d0 - (kt * 16 + j);
;         const bool bad = SEL ? (dist < 0) : ((unsigned)dist >= 512u);
; DI void attn_phase(const Params& p, const int layer, const int wid_s) {
;     ...
;         for (int si = 0; si < nsteps; ++si) {
;           asm volatile("s_waitcnt vmcnt(1) lgkmcnt(0)" ::: "memory");
;           __builtin_amdgcn_s_barrier();
;           asm volatile("" ::: "memory");
;           RING_ISSUE(si + 2);
;           const int kb = kb0 + si * 32;
;           if (kb > kmax_w || kb < lo_w) continue;
;           if (br == 1 && kb + 31 + 128 <= t0 && __ballot((selmask >> (kb >> 6)) & 1u) == 0ull) continue;
;           LAS unsigned char* slotp = ring + (si % 3) * 8192;
;           KF kv;
; #pragma unroll
;           for (int kt = 0; kt < 2; ++kt)
; #pragma unroll
;             for (int ks = 0; ks < 2; ++ks) kv.k[kt][ks] = *(const LAS half8*)(slotp + kread[kt][ks]);
; #pragma unroll
;           for (int dt = 0; dt < 4; ++dt) kv.v[dt] = *(const LAS half8*)(slotp + vread[dt]);
;           if (br == 1) {
;             const bool bit = (selmask >> (kb >> 6)) & 1u;
;             if (kb + 31 + 128 <= t0) attn_step<true, false>(kv, kb, t, lane, bit, tabh, q, O, nRs, l);
;             else attn_step<true, true>(kv, kb, t, lane, bit, tabh, q, O, nRs, l);
;           } else {
;             const bool gen = (kb + 31 + 128 > t0) || (kb + 512 <= t0 + 15);
;             if (!gen) attn_step<false, false>(kv, kb, t, lane, true, tabh, q, O, nRw, l);
;             else attn_step<false, true>(kv, kb, t, lane, true, tabh, q, O, nRw, l);
;           }
.Lat_cok_y1:
	s_bitcmp1_b32 s44, 0
	s_cbranch_scc0 .Lat_yb1
	s_waitcnt lgkmcnt(4)
	v_mfma_f32_16x16x32_f16 v[60:63], v[80:83], v[120:123], v[60:63]
	v_add_f32_e32 v214, v214, v198
	v_add_f32_e32 v215, v215, v199
	v_mfma_f32_16x16x32_f16 v[56:59], v[76:79], v[120:123], v[56:59]
	v_add_f32_e32 v216, v216, v200
	v_add_f32_e32 v217, v217, v201
	v_add_f32_e32 v214, v214, v202
	v_mfma_f32_16x16x32_f16 v[52:55], v[72:75], v[120:123], v[52:55]
	v_add_f32_e32 v215, v215, v203
	v_add_f32_e32 v216, v216, v204
	v_add_f32_e32 v217, v217, v205
	v_mfma_f32_16x16x32_f16 v[48:51], v[68:71], v[120:123], v[48:51]
	v_add_f32_e32 v218, v218, v206
	v_add_f32_e32 v219, v219, v207
	v_add_f32_e32 v220, v220, v208
	v_mfma_f32_16x16x32_f16 v[44:47], v[80:83], v[124:127], v[44:47]
	v_add_f32_e32 v221, v221, v209
	v_add_f32_e32 v218, v218, v210
	v_add_f32_e32 v219, v219, v211
	v_mfma_f32_16x16x32_f16 v[40:43], v[76:79], v[124:127], v[40:43]
	v_add_f32_e32 v220, v220, v212
	v_add_f32_e32 v221, v221, v213
	s_add_i32 s8, s45, 64
	v_mfma_f32_16x16x32_f16 v[36:39], v[72:75], v[124:127], v[36:39]
	s_min_i32 s8, s8, s14
	s_mul_i32 s8, s8, s42
	s_mov_b32 s9, 0
	v_mfma_f32_16x16x32_f16 v[32:35], v[68:71], v[124:127], v[32:35]
	s_add_i32 m0, s22, 0x20080
	v_lshl_add_u64 v[238:239], v[240:241], 0, s[8:9]
	global_load_lds_dwordx4 v[238:239], off
	s_waitcnt lgkmcnt(0)
	s_mov_b32 s44, s12
	v_mfma_f32_16x16x32_f16 v[100:103], v[96:99], v[8:11], v[128:131]
	s_add_i32 s45, s45, 32
	s_add_i32 s41, s41, -1
	v_mfma_f32_16x16x32_f16 v[104:107], v[88:91], v[8:11], v[128:131]
	s_cmp_gt_i32 s45, s39
	s_cselect_b32 s11, 2, 0
	s_cmp_le_i32 s45, s43
	v_mfma_f32_16x16x32_f16 v[108:111], v[96:99], v[16:19], v[132:135]
	s_cselect_b32 s10, 2, 0
	s_and_b32 s10, s10, s4
	v_mfma_f32_16x16x32_f16 v[112:115], v[88:91], v[16:19], v[132:135]
	s_or_b32 s11, s11, s10
	s_lshr_b32 s10, s45, 6
	v_bfe_u32 v66, v244, s10, 1
	v_mfma_f32_16x16x32_f16 v[100:103], v[92:95], v[12:15], v[100:103]
	v_cmp_ne_u32_e32 vcc, 0, v66
	s_cmp_lg_u64 vcc, 0
	v_mfma_f32_16x16x32_f16 v[104:107], v[84:87], v[12:15], v[104:107]
	s_cselect_b32 s10, 1, 0
	s_lshr_b32 s9, s11, 1
	s_or_b32 s10, s10, s9
	v_mfma_f32_16x16x32_f16 v[108:111], v[92:95], v[20:23], v[108:111]
	s_cmp_le_i32 s45, s15
	s_cselect_b32 s10, s10, 0
	v_mfma_f32_16x16x32_f16 v[112:115], v[84:87], v[20:23], v[112:115]
	s_cmp_ge_i32 s45, s40
	s_cselect_b32 s10, s10, 0
	s_or_b32 s12, s11, s10
	ds_read_b128 v[80:83], v65 offset:12288
	ds_read_b128 v[76:79], v65 offset:13312
	ds_read_b128 v[72:75], v65 offset:14336
	ds_read_b128 v[68:71], v65 offset:15360
	s_bitcmp1_b32 s44, 1
	s_cbranch_scc0 .Lat_noga_ya1
	v_add_f32_e32 v100, v100, v222
	v_add_f32_e32 v101, v101, v223
	v_add_f32_e32 v102, v102, v224
	v_add_f32_e32 v103, v103, v225
	v_add_f32_e32 v104, v104, v226
	v_add_f32_e32 v105, v105, v227
	v_add_f32_e32 v106, v106, v228
	v_add_f32_e32 v107, v107, v229
	v_add_f32_e32 v108, v108, v230
	v_add_f32_e32 v109, v109, v231
	v_add_f32_e32 v110, v110, v232
	v_add_f32_e32 v111, v111, v233
	v_add_f32_e32 v112, v112, v234
	v_add_f32_e32 v113, v113, v235
	v_add_f32_e32 v114, v114, v236
	v_add_f32_e32 v115, v115, v237

; template <bool SEL, bool GEN>
; DI void attn_step(const KF& kv, const int kb, const int t, const int lane, const bool selbit,
;                   const LAS float* tabh, const half8 (&q)[2][2], f32x4 (&O)[2][4], const float (&nR)[2], float (&l)[2]) {
;     ...
;   f32x4 s[2][2];
; #pragma unroll
;   for (int hp = 0; hp < 2; ++hp) {
;     float nm = nR[hp];
;     if (SEL) nm = selbit ? nm : MASKV;
;     const f32x4 c0 = {nm, nm, nm, nm};
; #pragma unroll
;     for (int kt = 0; kt < 2; ++kt) {
;       s[hp][kt] = MFMA16(kv.k[kt][0], q[hp][0], c0);
;       s[hp][kt] = MFMA16(kv.k[kt][1], q[hp][1], s[hp][kt]);
;     }
;   }
;   if (GEN) {
;     const int d0 = t - kb - fq * 4;
; #pragma unroll
;     for (int kt = 0; kt < 2; ++kt)
; #pragma unroll
;       for (int j = 0; j < 4; ++j) {
;         const int dist = d0 - (kt * 16 + j);
;         const bool bad = SEL ? (dist < 0) : ((unsigned)dist >= 512u);
; DI void attn_phase(const Params& p, const int layer, const int wid_s) {
;     ...
;         for (int si = 0; si < nsteps; ++si) {
;           asm volatile("s_waitcnt vmcnt(1) lgkmcnt(0)" ::: "memory");
;           __builtin_amdgcn_s_barrier();
;           asm volatile("" ::: "memory");
;           RING_ISSUE(si + 2);
;           const int kb = kb0 + si * 32;
;           if (kb > kmax_w || kb < lo_w) continue;
;           if (br == 1 && kb + 31 + 128 <= t0 && __ballot((selmask >> (kb >> 6)) & 1u) == 0ull) continue;
;           LAS unsigned char* slotp = ring + (si % 3) * 8192;
;           KF kv;
; #pragma unroll
;           for (int kt = 0; kt < 2; ++kt)
; #pragma unroll
;             for (int ks = 0; ks < 2; ++ks) kv.k[kt][ks] = *(const LAS half8*)(slotp + kread[kt][ks]);
; #pragma unroll
;           for (int dt = 0; dt < 4; ++dt) kv.v[dt] = *(const LAS half8*)(slotp + vread[dt]);
;           if (br == 1) {
;             const bool bit = (selmask >> (kb >> 6)) & 1u;
;             if (kb + 31 + 128 <= t0) attn_step<true, false>(kv, kb, t, lane, bit, tabh, q, O, nRs, l);
;             else attn_step<true, true>(kv, kb, t, lane, bit, tabh, q, O, nRs, l);
;           } else {
;             const bool gen = (kb + 31 + 128 > t0) || (kb + 512 <= t0 + 15);
;             if (!gen) attn_step<false, false>(kv, kb, t, lane, true, tabh, q, O, nRw, l);
;             else attn_step<false, true>(kv, kb, t, lane, true, tabh, q, O, nRw, l);
;           }
.Lat_yb1:
	s_waitcnt lgkmcnt(0)
	s_mov_b32 s44, s12
	v_mfma_f32_16x16x32_f16 v[100:103], v[96:99], v[8:11], v[128:131]
	s_add_i32 s8, s45, 64
	s_min_i32 s8, s8, s14
	s_mul_i32 s8, s8, s42
	v_mfma_f32_16x16x32_f16 v[104:107], v[88:91], v[8:11], v[128:131]
	s_mov_b32 s9, 0
	s_add_i32 m0, s22, 0x20080
	v_lshl_add_u64 v[238:239], v[240:241], 0, s[8:9]
	v_mfma_f32_16x16x32_f16 v[108:111], v[96:99], v[16:19], v[132:135]
	global_load_lds_dwordx4 v[238:239], off
	s_add_i32 s45, s45, 32
	s_add_i32 s41, s41, -1
	s_cmp_gt_i32 s45, s39
	v_mfma_f32_16x16x32_f16 v[112:115], v[88:91], v[16:19], v[132:135]
	s_cselect_b32 s11, 2, 0
	s_cmp_le_i32 s45, s43
	s_cselect_b32 s10, 2, 0
	v_mfma_f32_16x16x32_f16 v[100:103], v[92:95], v[12:15], v[100:103]
	s_and_b32 s10, s10, s4
	s_or_b32 s11, s11, s10
	s_lshr_b32 s10, s45, 6
	v_mfma_f32_16x16x32_f16 v[104:107], v[84:87], v[12:15], v[104:107]
	v_bfe_u32 v66, v244, s10, 1
	v_cmp_ne_u32_e32 vcc, 0, v66
	s_cmp_lg_u64 vcc, 0
	s_cselect_b32 s10, 1, 0
	v_mfma_f32_16x16x32_f16 v[108:111], v[92:95], v[20:23], v[108:111]
	s_lshr_b32 s9, s11, 1
	s_or_b32 s10, s10, s9
	s_cmp_le_i32 s45, s15
	v_mfma_f32_16x16x32_f16 v[112:115], v[84:87], v[20:23], v[112:115]
	s_cselect_b32 s10, s10, 0
	s_cmp_ge_i32 s45, s40
	s_cselect_b32 s10, s10, 0
	s_or_b32 s12, s11, s10
	ds_read_b128 v[80:83], v65 offset:12288
	ds_read_b128 v[76:79], v65 offset:13312
	ds_read_b128 v[72:75], v65 offset:14336
	ds_read_b128 v[68:71], v65 offset:15360
	s_bitcmp1_b32 s44, 1
	s_cbranch_scc0 .Lat_noga_yb1
	v_add_f32_e32 v100, v100, v222
	v_add_f32_e32 v101, v101, v223
	v_add_f32_e32 v102, v102, v224
	v_add_f32_e32 v103, v103, v225
	v_add_f32_e32 v104, v104, v226
	v_add_f32_e32 v105, v105, v227
	v_add_f32_e32 v106, v106, v228
	v_add_f32_e32 v107, v107, v229
	v_add_f32_e32 v108, v108, v230
	v_add_f32_e32 v109, v109, v231
	v_add_f32_e32 v110, v110, v232
	v_add_f32_e32 v111, v111, v233
	v_add_f32_e32 v112, v112, v234
	v_add_f32_e32 v113, v113, v235
	v_add_f32_e32 v114, v114, v236
	v_add_f32_e32 v115, v115, v237

; template <bool SEL, bool GEN>
; DI void attn_step(const KF& kv, const int kb, const int t, const int lane, const bool selbit,
;                   const LAS float* tabh, const half8 (&q)[2][2], f32x4 (&O)[2][4], const float (&nR)[2], float (&l)[2]) {
;     ...
;   f32x4 s[2][2];
; #pragma unroll
;   for (int hp = 0; hp < 2; ++hp) {
;     float nm = nR[hp];
;     if (SEL) nm = selbit ? nm : MASKV;
;     const f32x4 c0 = {nm, nm, nm, nm};
; #pragma unroll
;     for (int kt = 0; kt < 2; ++kt) {
;       s[hp][kt] = MFMA16(kv.k[kt][0], q[hp][0], c0);
;       s[hp][kt] = MFMA16(kv.k[kt][1], q[hp][1], s[hp][kt]);
;     }
;   }
;   if (GEN) {
;     const int d0 = t - kb - fq * 4;
; #pragma unroll
;     for (int kt = 0; kt < 2; ++kt)
; #pragma unroll
;       for (int j = 0; j < 4; ++j) {
;         const int dist = d0 - (kt * 16 + j);
;         const bool bad = SEL ? (dist < 0) : ((unsigned)dist >= 512u);
; DI void attn_phase(const Params& p, const int layer, const int wid_s) {
;     ...
;         for (int si = 0; si < nsteps; ++si) {
;           asm volatile("s_waitcnt vmcnt(1) lgkmcnt(0)" ::: "memory");
;           __builtin_amdgcn_s_barrier();
;           asm volatile("" ::: "memory");
;           RING_ISSUE(si + 2);
;           const int kb = kb0 + si * 32;
;           if (kb > kmax_w || kb < lo_w) continue;
;           if (br == 1 && kb + 31 + 128 <= t0 && __ballot((selmask >> (kb >> 6)) & 1u) == 0ull) continue;
;           LAS unsigned char* slotp = ring + (si % 3) * 8192;
;           KF kv;
; #pragma unroll
;           for (int kt = 0; kt < 2; ++kt)
; #pragma unroll
;             for (int ks = 0; ks < 2; ++ks) kv.k[kt][ks] = *(const LAS half8*)(slotp + kread[kt][ks]);
; #pragma unroll
;           for (int dt = 0; dt < 4; ++dt) kv.v[dt] = *(const LAS half8*)(slotp + vread[dt]);
;           if (br == 1) {
;             const bool bit = (selmask >> (kb >> 6)) & 1u;
;             if (kb + 31 + 128 <= t0) attn_step<true, false>(kv, kb, t, lane, bit, tabh, q, O, nRs, l);
;             else attn_step<true, true>(kv, kb, t, lane, bit, tabh, q, O, nRs, l);
;           } else {
;             const bool gen = (kb + 31 + 128 > t0) || (kb + 512 <= t0 + 15);
;             if (!gen) attn_step<false, false>(kv, kb, t, lane, true, tabh, q, O, nRw, l);
;             else attn_step<false, true>(kv, kb, t, lane, true, tabh, q, O, nRw, l);
;           }
.Lat_yskip1:
	s_bitcmp1_b32 s44, 0
	s_cbranch_scc0 .Lat_yd1
	s_waitcnt lgkmcnt(0)
	v_mfma_f32_16x16x32_f16 v[60:63], v[80:83], v[120:123], v[60:63]
	v_add_f32_e32 v214, v214, v198
	v_add_f32_e32 v215, v215, v199
	v_add_f32_e32 v216, v216, v200
	v_add_f32_e32 v217, v217, v201
	v_add_f32_e32 v214, v214, v202
	v_mfma_f32_16x16x32_f16 v[56:59], v[76:79], v[120:123], v[56:59]
	v_add_f32_e32 v215, v215, v203
	v_add_f32_e32 v216, v216, v204
	v_add_f32_e32 v217, v217, v205
	v_add_f32_e32 v218, v218, v206
	v_add_f32_e32 v219, v219, v207
	v_mfma_f32_16x16x32_f16 v[52:55], v[72:75], v[120:123], v[52:55]
	v_add_f32_e32 v220, v220, v208
	v_add_f32_e32 v221, v221, v209
	v_add_f32_e32 v218, v218, v210
	v_add_f32_e32 v219, v219, v211
	v_add_f32_e32 v220, v220, v212
	v_add_f32_e32 v221, v221, v213
	v_mfma_f32_16x16x32_f16 v[48:51], v[68:71], v[120:123], v[48:51]
	s_add_i32 s8, s45, 64
	s_min_i32 s8, s8, s14
	s_mul_i32 s8, s8, s42
	s_mov_b32 s9, 0
	s_add_i32 m0, s22, 0x20080
	v_mfma_f32_16x16x32_f16 v[44:47], v[80:83], v[124:127], v[44:47]
	v_lshl_add_u64 v[238:239], v[240:241], 0, s[8:9]
	global_load_lds_dwordx4 v[238:239], off
	s_add_i32 s45, s45, 32
	s_add_i32 s41, s41, -1
	s_cmp_gt_i32 s45, s39
	v_mfma_f32_16x16x32_f16 v[40:43], v[76:79], v[124:127], v[40:43]
	s_cselect_b32 s11, 2, 0
	s_cmp_le_i32 s45, s43
	s_cselect_b32 s10, 2, 0
	s_and_b32 s10, s10, s4
	s_or_b32 s11, s11, s10
	s_lshr_b32 s10, s45, 6
	v_mfma_f32_16x16x32_f16 v[36:39], v[72:75], v[124:127], v[36:39]
	v_bfe_u32 v66, v244, s10, 1
	v_cmp_ne_u32_e32 vcc, 0, v66
	s_cmp_lg_u64 vcc, 0
	s_cselect_b32 s10, 1, 0
	s_lshr_b32 s9, s11, 1
	v_mfma_f32_16x16x32_f16 v[32:35], v[68:71], v[124:127], v[32:35]
	s_or_b32 s10, s10, s9
	s_cmp_le_i32 s45, s15
	s_cselect_b32 s10, s10, 0
	s_cmp_ge_i32 s45, s40
	s_cselect_b32 s10, s10, 0
	s_or_b32 s12, s11, s10
	s_mov_b32 s44, 0
	s_cmp_lg_u32 s41, 0
	s_cbranch_scc1 .Lat_ytop2
	s_branch .Lat_yexit

; template <bool SEL, bool GEN>
; DI void attn_step(const KF& kv, const int kb, const int t, const int lane, const bool selbit,
;                   const LAS float* tabh, const half8 (&q)[2][2], f32x4 (&O)[2][4], const float (&nR)[2], float (&l)[2]) {
;     ...
;   f32x4 s[2][2];
; #pragma unroll
;   for (int hp = 0; hp < 2; ++hp) {
;     float nm = nR[hp];
;     if (SEL) nm = selbit ? nm : MASKV;
;     const f32x4 c0 = {nm, nm, nm, nm};
; #pragma unroll
;     for (int kt = 0; kt < 2; ++kt) {
;       s[hp][kt] = MFMA16(kv.k[kt][0], q[hp][0], c0);
;       s[hp][kt] = MFMA16(kv.k[kt][1], q[hp][1], s[hp][kt]);
;     }
;   }
;   if (GEN) {
;     const int d0 = t - kb - fq * 4;
; #pragma unroll
;     for (int kt = 0; kt < 2; ++kt)
; #pragma unroll
;       for (int j = 0; j < 4; ++j) {
;         const int dist = d0 - (kt * 16 + j);
;         const bool bad = SEL ? (dist < 0) : ((unsigned)dist >= 512u);
; DI void attn_phase(const Params& p, const int layer, const int wid_s) {
;     ...
;         for (int si = 0; si < nsteps; ++si) {
;           asm volatile("s_waitcnt vmcnt(1) lgkmcnt(0)" ::: "memory");
;           __builtin_amdgcn_s_barrier();
;           asm volatile("" ::: "memory");
;           RING_ISSUE(si + 2);
;           const int kb = kb0 + si * 32;
;           if (kb > kmax_w || kb < lo_w) continue;
;           if (br == 1 && kb + 31 + 128 <= t0 && __ballot((selmask >> (kb >> 6)) & 1u) == 0ull) continue;
;           LAS unsigned char* slotp = ring + (si % 3) * 8192;
;           KF kv;
; #pragma unroll
;           for (int kt = 0; kt < 2; ++kt)
; #pragma unroll
;             for (int ks = 0; ks < 2; ++ks) kv.k[kt][ks] = *(const LAS half8*)(slotp + kread[kt][ks]);
; #pragma unroll
;           for (int dt = 0; dt < 4; ++dt) kv.v[dt] = *(const LAS half8*)(slotp + vread[dt]);
;           if (br == 1) {
;             const bool bit = (selmask >> (kb >> 6)) & 1u;
;             if (kb + 31 + 128 <= t0) attn_step<true, false>(kv, kb, t, lane, bit, tabh, q, O, nRs, l);
;             else attn_step<true, true>(kv, kb, t, lane, bit, tabh, q, O, nRs, l);
;           } else {
;             const bool gen = (kb + 31 + 128 > t0) || (kb + 512 <= t0 + 15);
;             if (!gen) attn_step<false, false>(kv, kb, t, lane, true, tabh, q, O, nRw, l);
;             else attn_step<false, true>(kv, kb, t, lane, true, tabh, q, O, nRw, l);
;           }
.Lat_cok_y2:
	s_bitcmp1_b32 s44, 0
	s_cbranch_scc0 .Lat_yb2
	s_waitcnt lgkmcnt(4)
	v_mfma_f32_16x16x32_f16 v[60:63], v[80:83], v[120:123], v[60:63]
	v_add_f32_e32 v214, v214, v198
	v_add_f32_e32 v215, v215, v199
	v_mfma_f32_16x16x32_f16 v[56:59], v[76:79], v[120:123], v[56:59]
	v_add_f32_e32 v216, v216, v200
	v_add_f32_e32 v217, v217, v201
	v_add_f32_e32 v214, v214, v202
	v_mfma_f32_16x16x32_f16 v[52:55], v[72:75], v[120:123], v[52:55]
	v_add_f32_e32 v215, v215, v203
	v_add_f32_e32 v216, v216, v204
	v_add_f32_e32 v217, v217, v205
	v_mfma_f32_16x16x32_f16 v[48:51], v[68:71], v[120:123], v[48:51]
	v_add_f32_e32 v218, v218, v206
	v_add_f32_e32 v219, v219, v207
	v_add_f32_e32 v220, v220, v208
	v_mfma_f32_16x16x32_f16 v[44:47], v[80:83], v[124:127], v[44:47]
	v_add_f32_e32 v221, v221, v209
	v_add_f32_e32 v218, v218, v210
	v_add_f32_e32 v219, v219, v211
	v_mfma_f32_16x16x32_f16 v[40:43], v[76:79], v[124:127], v[40:43]
	v_add_f32_e32 v220, v220, v212
	v_add_f32_e32 v221, v221, v213
	s_add_i32 s8, s45, 64
	v_mfma_f32_16x16x32_f16 v[36:39], v[72:75], v[124:127], v[36:39]
	s_min_i32 s8, s8, s14
	s_mul_i32 s8, s8, s42
	s_mov_b32 s9, 0
	v_mfma_f32_16x16x32_f16 v[32:35], v[68:71], v[124:127], v[32:35]
	s_add_i32 m0, s22, 0x19880
	v_lshl_add_u64 v[238:239], v[240:241], 0, s[8:9]
	global_load_lds_dwordx4 v[238:239], off
	s_waitcnt lgkmcnt(0)
	s_mov_b32 s44, s12
	v_mfma_f32_16x16x32_f16 v[100:103], v[96:99], v[8:11], v[128:131]
	s_add_i32 s45, s45, 32
	s_add_i32 s41, s41, -1
	v_mfma_f32_16x16x32_f16 v[104:107], v[88:91], v[8:11], v[128:131]
	s_cmp_gt_i32 s45, s39
	s_cselect_b32 s11, 2, 0
	s_cmp_le_i32 s45, s43
	v_mfma_f32_16x16x32_f16 v[108:111], v[96:99], v[16:19], v[132:135]
	s_cselect_b32 s10, 2, 0
	s_and_b32 s10, s10, s4
	v_mfma_f32_16x16x32_f16 v[112:115], v[88:91], v[16:19], v[132:135]
	s_or_b32 s11, s11, s10
	s_lshr_b32 s10, s45, 6
	v_bfe_u32 v66, v244, s10, 1
	v_mfma_f32_16x16x32_f16 v[100:103], v[92:95], v[12:15], v[100:103]
	v_cmp_ne_u32_e32 vcc, 0, v66
	s_cmp_lg_u64 vcc, 0
	v_mfma_f32_16x16x32_f16 v[104:107], v[84:87], v[12:15], v[104:107]
	s_cselect_b32 s10, 1, 0
	s_lshr_b32 s9, s11, 1
	s_or_b32 s10, s10, s9
	v_mfma_f32_16x16x32_f16 v[108:111], v[92:95], v[20:23], v[108:111]
	s_cmp_le_i32 s45, s15
	s_cselect_b32 s10, s10, 0
	v_mfma_f32_16x16x32_f16 v[112:115], v[84:87], v[20:23], v[112:115]
	s_cmp_ge_i32 s45, s40
	s_cselect_b32 s10, s10, 0
	s_or_b32 s12, s11, s10
	ds_read_b128 v[80:83], v65 offset:20480
	ds_read_b128 v[76:79], v65 offset:21504
	ds_read_b128 v[72:75], v65 offset:22528
	ds_read_b128 v[68:71], v65 offset:23552
	s_bitcmp1_b32 s44, 1
	s_cbranch_scc0 .Lat_noga_ya2
	v_add_f32_e32 v100, v100, v222
	v_add_f32_e32 v101, v101, v223
	v_add_f32_e32 v102, v102, v224
	v_add_f32_e32 v103, v103, v225
	v_add_f32_e32 v104, v104, v226
	v_add_f32_e32 v105, v105, v227
	v_add_f32_e32 v106, v106, v228
	v_add_f32_e32 v107, v107, v229
	v_add_f32_e32 v108, v108, v230
	v_add_f32_e32 v109, v109, v231
	v_add_f32_e32 v110, v110, v232
	v_add_f32_e32 v111, v111, v233
	v_add_f32_e32 v112, v112, v234
	v_add_f32_e32 v113, v113, v235
	v_add_f32_e32 v114, v114, v236
	v_add_f32_e32 v115, v115, v237

; template <bool SEL, bool GEN>
; DI void attn_step(const KF& kv, const int kb, const int t, const int lane, const bool selbit,
;                   const LAS float* tabh, const half8 (&q)[2][2], f32x4 (&O)[2][4], const float (&nR)[2], float (&l)[2]) {
;     ...
;   f32x4 s[2][2];
; #pragma unroll
;   for (int hp = 0; hp < 2; ++hp) {
;     float nm = nR[hp];
;     if (SEL) nm = selbit ? nm : MASKV;
;     const f32x4 c0 = {nm, nm, nm, nm};
; #pragma unroll
;     for (int kt = 0; kt < 2; ++kt) {
;       s[hp][kt] = MFMA16(kv.k[kt][0], q[hp][0], c0);
;       s[hp][kt] = MFMA16(kv.k[kt][1], q[hp][1], s[hp][kt]);
;     }
;   }
;   if (GEN) {
;     const int d0 = t - kb - fq * 4;
; #pragma unroll
;     for (int kt = 0; kt < 2; ++kt)
; #pragma unroll
;       for (int j = 0; j < 4; ++j) {
;         const int dist = d0 - (kt * 16 + j);
;         const bool bad = SEL ? (dist < 0) : ((unsigned)dist >= 512u);
; DI void attn_phase(const Params& p, const int layer, const int wid_s) {
;     ...
;         for (int si = 0; si < nsteps; ++si) {
;           asm volatile("s_waitcnt vmcnt(1) lgkmcnt(0)" ::: "memory");
;           __builtin_amdgcn_s_barrier();
;           asm volatile("" ::: "memory");
;           RING_ISSUE(si + 2);
;           const int kb = kb0 + si * 32;
;           if (kb > kmax_w || kb < lo_w) continue;
;           if (br == 1 && kb + 31 + 128 <= t0 && __ballot((selmask >> (kb >> 6)) & 1u) == 0ull) continue;
;           LAS unsigned char* slotp = ring + (si % 3) * 8192;
;           KF kv;
; #pragma unroll
;           for (int kt = 0; kt < 2; ++kt)
; #pragma unroll
;             for (int ks = 0; ks < 2; ++ks) kv.k[kt][ks] = *(const LAS half8*)(slotp + kread[kt][ks]);
; #pragma unroll
;           for (int dt = 0; dt < 4; ++dt) kv.v[dt] = *(const LAS half8*)(slotp + vread[dt]);
;           if (br == 1) {
;             const bool bit = (selmask >> (kb >> 6)) & 1u;
;             if (kb + 31 + 128 <= t0) attn_step<true, false>(kv, kb, t, lane, bit, tabh, q, O, nRs, l);
;             else attn_step<true, true>(kv, kb, t, lane, bit, tabh, q, O, nRs, l);
;           } else {
;             const bool gen = (kb + 31 + 128 > t0) || (kb + 512 <= t0 + 15);
;             if (!gen) attn_step<false, false>(kv, kb, t, lane, true, tabh, q, O, nRw, l);
;             else attn_step<false, true>(kv, kb, t, lane, true, tabh, q, O, nRw, l);
;           }
.Lat_yb2:
	s_waitcnt lgkmcnt(0)
	s_mov_b32 s44, s12
	v_mfma_f32_16x16x32_f16 v[100:103], v[96:99], v[8:11], v[128:131]
	s_add_i32 s8, s45, 64
	s_min_i32 s8, s8, s14
	s_mul_i32 s8, s8, s42
	v_mfma_f32_16x16x32_f16 v[104:107], v[88:91], v[8:11], v[128:131]
	s_mov_b32 s9, 0
	s_add_i32 m0, s22, 0x19880
	v_lshl_add_u64 v[238:239], v[240:241], 0, s[8:9]
	v_mfma_f32_16x16x32_f16 v[108:111], v[96:99], v[16:19], v[132:135]
	global_load_lds_dwordx4 v[238:239], off
	s_add_i32 s45, s45, 32
	s_add_i32 s41, s41, -1
	s_cmp_gt_i32 s45, s39
	v_mfma_f32_16x16x32_f16 v[112:115], v[88:91], v[16:19], v[132:135]
	s_cselect_b32 s11, 2, 0
	s_cmp_le_i32 s45, s43
	s_cselect_b32 s10, 2, 0
	v_mfma_f32_16x16x32_f16 v[100:103], v[92:95], v[12:15], v[100:103]
	s_and_b32 s10, s10, s4
	s_or_b32 s11, s11, s10
	s_lshr_b32 s10, s45, 6
	v_mfma_f32_16x16x32_f16 v[104:107], v[84:87], v[12:15], v[104:107]
	v_bfe_u32 v66, v244, s10, 1
	v_cmp_ne_u32_e32 vcc, 0, v66
	s_cmp_lg_u64 vcc, 0
	s_cselect_b32 s10, 1, 0
	v_mfma_f32_16x16x32_f16 v[108:111], v[92:95], v[20:23], v[108:111]
	s_lshr_b32 s9, s11, 1
	s_or_b32 s10, s10, s9
	s_cmp_le_i32 s45, s15
	v_mfma_f32_16x16x32_f16 v[112:115], v[84:87], v[20:23], v[112:115]
	s_cselect_b32 s10, s10, 0
	s_cmp_ge_i32 s45, s40
	s_cselect_b32 s10, s10, 0
	s_or_b32 s12, s11, s10
	ds_read_b128 v[80:83], v65 offset:20480
	ds_read_b128 v[76:79], v65 offset:21504
	ds_read_b128 v[72:75], v65 offset:22528
	ds_read_b128 v[68:71], v65 offset:23552
	s_bitcmp1_b32 s44, 1
	s_cbranch_scc0 .Lat_noga_yb2
	v_add_f32_e32 v100, v100, v222
	v_add_f32_e32 v101, v101, v223
	v_add_f32_e32 v102, v102, v224
	v_add_f32_e32 v103, v103, v225
	v_add_f32_e32 v104, v104, v226
	v_add_f32_e32 v105, v105, v227
	v_add_f32_e32 v106, v106, v228
	v_add_f32_e32 v107, v107, v229
	v_add_f32_e32 v108, v108, v230
	v_add_f32_e32 v109, v109, v231
	v_add_f32_e32 v110, v110, v232
	v_add_f32_e32 v111, v111, v233
	v_add_f32_e32 v112, v112, v234
	v_add_f32_e32 v113, v113, v235
	v_add_f32_e32 v114, v114, v236
	v_add_f32_e32 v115, v115, v237

; template <bool SEL, bool GEN>
; DI void attn_step(const KF& kv, const int kb, const int t, const int lane, const bool selbit,
;                   const LAS float* tabh, const half8 (&q)[2][2], f32x4 (&O)[2][4], const float (&nR)[2], float (&l)[2]) {
;     ...
;   f32x4 s[2][2];
; #pragma unroll
;   for (int hp = 0; hp < 2; ++hp) {
;     float nm = nR[hp];
;     if (SEL) nm = selbit ? nm : MASKV;
;     const f32x4 c0 = {nm, nm, nm, nm};
; #pragma unroll
;     for (int kt = 0; kt < 2; ++kt) {
;       s[hp][kt] = MFMA16(kv.k[kt][0], q[hp][0], c0);
;       s[hp][kt] = MFMA16(kv.k[kt][1], q[hp][1], s[hp][kt]);
;     }
;   }
;   if (GEN) {
;     const int d0 = t - kb - fq * 4;
; #pragma unroll
;     for (int kt = 0; kt < 2; ++kt)
; #pragma unroll
;       for (int j = 0; j < 4; ++j) {
;         const int dist = d0 - (kt * 16 + j);
;         const bool bad = SEL ? (dist < 0) : ((unsigned)dist >= 512u);
; DI void attn_phase(const Params& p, const int layer, const int wid_s) {
;     ...
;         for (int si = 0; si < nsteps; ++si) {
;           asm volatile("s_waitcnt vmcnt(1) lgkmcnt(0)" ::: "memory");
;           __builtin_amdgcn_s_barrier();
;           asm volatile("" ::: "memory");
;           RING_ISSUE(si + 2);
;           const int kb = kb0 + si * 32;
;           if (kb > kmax_w || kb < lo_w) continue;
;           if (br == 1 && kb + 31 + 128 <= t0 && __ballot((selmask >> (kb >> 6)) & 1u) == 0ull) continue;
;           LAS unsigned char* slotp = ring + (si % 3) * 8192;
;           KF kv;
; #pragma unroll
;           for (int kt = 0; kt < 2; ++kt)
; #pragma unroll
;             for (int ks = 0; ks < 2; ++ks) kv.k[kt][ks] = *(const LAS half8*)(slotp + kread[kt][ks]);
; #pragma unroll
;           for (int dt = 0; dt < 4; ++dt) kv.v[dt] = *(const LAS half8*)(slotp + vread[dt]);
;           if (br == 1) {
;             const bool bit = (selmask >> (kb >> 6)) & 1u;
;             if (kb + 31 + 128 <= t0) attn_step<true, false>(kv, kb, t, lane, bit, tabh, q, O, nRs, l);
;             else attn_step<true, true>(kv, kb, t, lane, bit, tabh, q, O, nRs, l);
;           } else {
;             const bool gen = (kb + 31 + 128 > t0) || (kb + 512 <= t0 + 15);
;             if (!gen) attn_step<false, false>(kv, kb, t, lane, true, tabh, q, O, nRw, l);
;             else attn_step<false, true>(kv, kb, t, lane, true, tabh, q, O, nRw, l);
;           }
.Lat_yskip2:
	s_bitcmp1_b32 s44, 0
	s_cbranch_scc0 .Lat_yd2
	s_waitcnt lgkmcnt(0)
	v_mfma_f32_16x16x32_f16 v[60:63], v[80:83], v[120:123], v[60:63]
	v_add_f32_e32 v214, v214, v198
	v_add_f32_e32 v215, v215, v199
	v_add_f32_e32 v216, v216, v200
	v_add_f32_e32 v217, v217, v201
	v_add_f32_e32 v214, v214, v202
	v_mfma_f32_16x16x32_f16 v[56:59], v[76:79], v[120:123], v[56:59]
	v_add_f32_e32 v215, v215, v203
	v_add_f32_e32 v216, v216, v204
	v_add_f32_e32 v217, v217, v205
	v_add_f32_e32 v218, v218, v206
	v_add_f32_e32 v219, v219, v207
	v_mfma_f32_16x16x32_f16 v[52:55], v[72:75], v[120:123], v[52:55]
	v_add_f32_e32 v220, v220, v208
	v_add_f32_e32 v221, v221, v209
	v_add_f32_e32 v218, v218, v210
	v_add_f32_e32 v219, v219, v211
	v_add_f32_e32 v220, v220, v212
	v_add_f32_e32 v221, v221, v213
	v_mfma_f32_16x16x32_f16 v[48:51], v[68:71], v[120:123], v[48:51]
	s_add_i32 s8, s45, 64
	s_min_i32 s8, s8, s14
	s_mul_i32 s8, s8, s42
	s_mov_b32 s9, 0
	s_add_i32 m0, s22, 0x19880
	v_mfma_f32_16x16x32_f16 v[44:47], v[80:83], v[124:127], v[44:47]
	v_lshl_add_u64 v[238:239], v[240:241], 0, s[8:9]
	global_load_lds_dwordx4 v[238:239], off
	s_add_i32 s45, s45, 32
	s_add_i32 s41, s41, -1
	s_cmp_gt_i32 s45, s39
	v_mfma_f32_16x16x32_f16 v[40:43], v[76:79], v[124:127], v[40:43]
	s_cselect_b32 s11, 2, 0
	s_cmp_le_i32 s45, s43
	s_cselect_b32 s10, 2, 0
	s_and_b32 s10, s10, s4
	s_or_b32 s11, s11, s10
	s_lshr_b32 s10, s45, 6
	v_mfma_f32_16x16x32_f16 v[36:39], v[72:75], v[124:127], v[36:39]
	v_bfe_u32 v66, v244, s10, 1
	v_cmp_ne_u32_e32 vcc, 0, v66
	s_cmp_lg_u64 vcc, 0
	s_cselect_b32 s10, 1, 0
	s_lshr_b32 s9, s11, 1
	v_mfma_f32_16x16x32_f16 v[32:35], v[68:71], v[124:127], v[32:35]
	s_or_b32 s10, s10, s9
	s_cmp_le_i32 s45, s15
	s_cselect_b32 s10, s10, 0
	s_cmp_ge_i32 s45, s40
	s_cselect_b32 s10, s10, 0
	s_or_b32 s12, s11, s10
	s_mov_b32 s44, 0
	s_cmp_lg_u32 s41, 0
	s_cbranch_scc1 .Lat_ytop3
	s_branch .Lat_yexit

; template <bool SEL, bool GEN>
; DI void attn_step(const KF& kv, const int kb, const int t, const int lane, const bool selbit,
;                   const LAS float* tabh, const half8 (&q)[2][2], f32x4 (&O)[2][4], const float (&nR)[2], float (&l)[2]) {
;     ...
;   f32x4 s[2][2];
; #pragma unroll
;   for (int hp = 0; hp < 2; ++hp) {
;     float nm = nR[hp];
;     if (SEL) nm = selbit ? nm : MASKV;
;     const f32x4 c0 = {nm, nm, nm, nm};
; #pragma unroll
;     for (int kt = 0; kt < 2; ++kt) {
;       s[hp][kt] = MFMA16(kv.k[kt][0], q[hp][0], c0);
;       s[hp][kt] = MFMA16(kv.k[kt][1], q[hp][1], s[hp][kt]);
;     }
;   }
;   if (GEN) {
;     const int d0 = t - kb - fq * 4;
; #pragma unroll
;     for (int kt = 0; kt < 2; ++kt)
; #pragma unroll
;       for (int j = 0; j < 4; ++j) {
;         const int dist = d0 - (kt * 16 + j);
;         const bool bad = SEL ? (dist < 0) : ((unsigned)dist >= 512u);
; DI void attn_phase(const Params& p, const int layer, const int wid_s) {
;     ...
;         for (int si = 0; si < nsteps; ++si) {
;           asm volatile("s_waitcnt vmcnt(1) lgkmcnt(0)" ::: "memory");
;           __builtin_amdgcn_s_barrier();
;           asm volatile("" ::: "memory");
;           RING_ISSUE(si + 2);
;           const int kb = kb0 + si * 32;
;           if (kb > kmax_w || kb < lo_w) continue;
;           if (br == 1 && kb + 31 + 128 <= t0 && __ballot((selmask >> (kb >> 6)) & 1u) == 0ull) continue;
;           LAS unsigned char* slotp = ring + (si % 3) * 8192;
;           KF kv;
; #pragma unroll
;           for (int kt = 0; kt < 2; ++kt)
; #pragma unroll
;             for (int ks = 0; ks < 2; ++ks) kv.k[kt][ks] = *(const LAS half8*)(slotp + kread[kt][ks]);
; #pragma unroll
;           for (int dt = 0; dt < 4; ++dt) kv.v[dt] = *(const LAS half8*)(slotp + vread[dt]);
;           if (br == 1) {
;             const bool bit = (selmask >> (kb >> 6)) & 1u;
;             if (kb + 31 + 128 <= t0) attn_step<true, false>(kv, kb, t, lane, bit, tabh, q, O, nRs, l);
;             else attn_step<true, true>(kv, kb, t, lane, bit, tabh, q, O, nRs, l);
;           } else {
;             const bool gen = (kb + 31 + 128 > t0) || (kb + 512 <= t0 + 15);
;             if (!gen) attn_step<false, false>(kv, kb, t, lane, true, tabh, q, O, nRw, l);
;             else attn_step<false, true>(kv, kb, t, lane, true, tabh, q, O, nRw, l);
;           }
.Lat_cok_y3:
	s_bitcmp1_b32 s44, 0
	s_cbranch_scc0 .Lat_yb3
	s_waitcnt lgkmcnt(4)
	v_mfma_f32_16x16x32_f16 v[60:63], v[80:83], v[120:123], v[60:63]
	v_add_f32_e32 v214, v214, v198
	v_add_f32_e32 v215, v215, v199
	v_mfma_f32_16x16x32_f16 v[56:59], v[76:79], v[120:123], v[56:59]
	v_add_f32_e32 v216, v216, v200
	v_add_f32_e32 v217, v217, v201
	v_add_f32_e32 v214, v214, v202
	v_mfma_f32_16x16x32_f16 v[52:55], v[72:75], v[120:123], v[52:55]
	v_add_f32_e32 v215, v215, v203
	v_add_f32_e32 v216, v216, v204
	v_add_f32_e32 v217, v217, v205
	v_mfma_f32_16x16x32_f16 v[48:51], v[68:71], v[120:123], v[48:51]
	v_add_f32_e32 v218, v218, v206
	v_add_f32_e32 v219, v219, v207
	v_add_f32_e32 v220, v220, v208
	v_mfma_f32_16x16x32_f16 v[44:47], v[80:83], v[124:127], v[44:47]
	v_add_f32_e32 v221, v221, v209
	v_add_f32_e32 v218, v218, v210
	v_add_f32_e32 v219, v219, v211
	v_mfma_f32_16x16x32_f16 v[40:43], v[76:79], v[124:127], v[40:43]
	v_add_f32_e32 v220, v220, v212
	v_add_f32_e32 v221, v221, v213
	s_add_i32 s8, s45, 64
	v_mfma_f32_16x16x32_f16 v[36:39], v[72:75], v[124:127], v[36:39]
	s_min_i32 s8, s8, s14
	s_mul_i32 s8, s8, s42
	s_mov_b32 s9, 0
	v_mfma_f32_16x16x32_f16 v[32:35], v[68:71], v[124:127], v[32:35]
	s_add_i32 m0, s22, 0x1b880
	v_lshl_add_u64 v[238:239], v[240:241], 0, s[8:9]
	global_load_lds_dwordx4 v[238:239], off
	s_waitcnt lgkmcnt(0)
	s_mov_b32 s44, s12
	v_mfma_f32_16x16x32_f16 v[100:103], v[96:99], v[8:11], v[128:131]
	s_add_i32 s45, s45, 32
	s_add_i32 s41, s41, -1
	v_mfma_f32_16x16x32_f16 v[104:107], v[88:91], v[8:11], v[128:131]
	s_cmp_gt_i32 s45, s39
	s_cselect_b32 s11, 2, 0
	s_cmp_le_i32 s45, s43
	v_mfma_f32_16x16x32_f16 v[108:111], v[96:99], v[16:19], v[132:135]
	s_cselect_b32 s10, 2, 0
	s_and_b32 s10, s10, s4
	v_mfma_f32_16x16x32_f16 v[112:115], v[88:91], v[16:19], v[132:135]
	s_or_b32 s11, s11, s10
	s_lshr_b32 s10, s45, 6
	v_bfe_u32 v66, v244, s10, 1
	v_mfma_f32_16x16x32_f16 v[100:103], v[92:95], v[12:15], v[100:103]
	v_cmp_ne_u32_e32 vcc, 0, v66
	s_cmp_lg_u64 vcc, 0
	v_mfma_f32_16x16x32_f16 v[104:107], v[84:87], v[12:15], v[104:107]
	s_cselect_b32 s10, 1, 0
	s_lshr_b32 s9, s11, 1
	s_or_b32 s10, s10, s9
	v_mfma_f32_16x16x32_f16 v[108:111], v[92:95], v[20:23], v[108:111]
	s_cmp_le_i32 s45, s15
	s_cselect_b32 s10, s10, 0
	v_mfma_f32_16x16x32_f16 v[112:115], v[84:87], v[20:23], v[112:115]
	s_cmp_ge_i32 s45, s40
	s_cselect_b32 s10, s10, 0
	s_or_b32 s12, s11, s10
	ds_read_b128 v[80:83], v65 offset:30720
	ds_read_b128 v[76:79], v65 offset:31744
	ds_read_b128 v[72:75], v65 offset:32768
	ds_read_b128 v[68:71], v65 offset:33792
	s_bitcmp1_b32 s44, 1
	s_cbranch_scc0 .Lat_noga_ya3
	v_add_f32_e32 v100, v100, v222
	v_add_f32_e32 v101, v101, v223
	v_add_f32_e32 v102, v102, v224
	v_add_f32_e32 v103, v103, v225
	v_add_f32_e32 v104, v104, v226
	v_add_f32_e32 v105, v105, v227
	v_add_f32_e32 v106, v106, v228
	v_add_f32_e32 v107, v107, v229
	v_add_f32_e32 v108, v108, v230
	v_add_f32_e32 v109, v109, v231
	v_add_f32_e32 v110, v110, v232
	v_add_f32_e32 v111, v111, v233
	v_add_f32_e32 v112, v112, v234
	v_add_f32_e32 v113, v113, v235
	v_add_f32_e32 v114, v114, v236
	v_add_f32_e32 v115, v115, v237

; template <bool SEL, bool GEN>
; DI void attn_step(const KF& kv, const int kb, const int t, const int lane, const bool selbit,
;                   const LAS float* tabh, const half8 (&q)[2][2], f32x4 (&O)[2][4], const float (&nR)[2], float (&l)[2]) {
;     ...
;   f32x4 s[2][2];
; #pragma unroll
;   for (int hp = 0; hp < 2; ++hp) {
;     float nm = nR[hp];
;     if (SEL) nm = selbit ? nm : MASKV;
;     const f32x4 c0 = {nm, nm, nm, nm};
; #pragma unroll
;     for (int kt = 0; kt < 2; ++kt) {
;       s[hp][kt] = MFMA16(kv.k[kt][0], q[hp][0], c0);
;       s[hp][kt] = MFMA16(kv.k[kt][1], q[hp][1], s[hp][kt]);
;     }
;   }
;   if (GEN) {
;     const int d0 = t - kb - fq * 4;
; #pragma unroll
;     for (int kt = 0; kt < 2; ++kt)
; #pragma unroll
;       for (int j = 0; j < 4; ++j) {
;         const int dist = d0 - (kt * 16 + j);
;         const bool bad = SEL ? (dist < 0) : ((unsigned)dist >= 512u);
; DI void attn_phase(const Params& p, const int layer, const int wid_s) {
;     ...
;         for (int si = 0; si < nsteps; ++si) {
;           asm volatile("s_waitcnt vmcnt(1) lgkmcnt(0)" ::: "memory");
;           __builtin_amdgcn_s_barrier();
;           asm volatile("" ::: "memory");
;           RING_ISSUE(si + 2);
;           const int kb = kb0 + si * 32;
;           if (kb > kmax_w || kb < lo_w) continue;
;           if (br == 1 && kb + 31 + 128 <= t0 && __ballot((selmask >> (kb >> 6)) & 1u) == 0ull) continue;
;           LAS unsigned char* slotp = ring + (si % 3) * 8192;
;           KF kv;
; #pragma unroll
;           for (int kt = 0; kt < 2; ++kt)
; #pragma unroll
;             for (int ks = 0; ks < 2; ++ks) kv.k[kt][ks] = *(const LAS half8*)(slotp + kread[kt][ks]);
; #pragma unroll
;           for (int dt = 0; dt < 4; ++dt) kv.v[dt] = *(const LAS half8*)(slotp + vread[dt]);
;           if (br == 1) {
;             const bool bit = (selmask >> (kb >> 6)) & 1u;
;             if (kb + 31 + 128 <= t0) attn_step<true, false>(kv, kb, t, lane, bit, tabh, q, O, nRs, l);
;             else attn_step<true, true>(kv, kb, t, lane, bit, tabh, q, O, nRs, l);
;           } else {
;             const bool gen = (kb + 31 + 128 > t0) || (kb + 512 <= t0 + 15);
;             if (!gen) attn_step<false, false>(kv, kb, t, lane, true, tabh, q, O, nRw, l);
;             else attn_step<false, true>(kv, kb, t, lane, true, tabh, q, O, nRw, l);
;           }
.Lat_yb3:
	s_waitcnt lgkmcnt(0)
	s_mov_b32 s44, s12
	v_mfma_f32_16x16x32_f16 v[100:103], v[96:99], v[8:11], v[128:131]
	s_add_i32 s8, s45, 64
	s_min_i32 s8, s8, s14
	s_mul_i32 s8, s8, s42
	v_mfma_f32_16x16x32_f16 v[104:107], v[88:91], v[8:11], v[128:131]
	s_mov_b32 s9, 0
	s_add_i32 m0, s22, 0x1b880
	v_lshl_add_u64 v[238:239], v[240:241], 0, s[8:9]
	v_mfma_f32_16x16x32_f16 v[108:111], v[96:99], v[16:19], v[132:135]
	global_load_lds_dwordx4 v[238:239], off
	s_add_i32 s45, s45, 32
	s_add_i32 s41, s41, -1
	s_cmp_gt_i32 s45, s39
	v_mfma_f32_16x16x32_f16 v[112:115], v[88:91], v[16:19], v[132:135]
	s_cselect_b32 s11, 2, 0
	s_cmp_le_i32 s45, s43
	s_cselect_b32 s10, 2, 0
	v_mfma_f32_16x16x32_f16 v[100:103], v[92:95], v[12:15], v[100:103]
	s_and_b32 s10, s10, s4
	s_or_b32 s11, s11, s10
	s_lshr_b32 s10, s45, 6
	v_mfma_f32_16x16x32_f16 v[104:107], v[84:87], v[12:15], v[104:107]
	v_bfe_u32 v66, v244, s10, 1
	v_cmp_ne_u32_e32 vcc, 0, v66
	s_cmp_lg_u64 vcc, 0
	s_cselect_b32 s10, 1, 0
	v_mfma_f32_16x16x32_f16 v[108:111], v[92:95], v[20:23], v[108:111]
	s_lshr_b32 s9, s11, 1
	s_or_b32 s10, s10, s9
	s_cmp_le_i32 s45, s15
	v_mfma_f32_16x16x32_f16 v[112:115], v[84:87], v[20:23], v[112:115]
	s_cselect_b32 s10, s10, 0
	s_cmp_ge_i32 s45, s40
	s_cselect_b32 s10, s10, 0
	s_or_b32 s12, s11, s10
	ds_read_b128 v[80:83], v65 offset:30720
	ds_read_b128 v[76:79], v65 offset:31744
	ds_read_b128 v[72:75], v65 offset:32768
	ds_read_b128 v[68:71], v65 offset:33792
	s_bitcmp1_b32 s44, 1
	s_cbranch_scc0 .Lat_noga_yb3
	v_add_f32_e32 v100, v100, v222
	v_add_f32_e32 v101, v101, v223
	v_add_f32_e32 v102, v102, v224
	v_add_f32_e32 v103, v103, v225
	v_add_f32_e32 v104, v104, v226
	v_add_f32_e32 v105, v105, v227
	v_add_f32_e32 v106, v106, v228
	v_add_f32_e32 v107, v107, v229
	v_add_f32_e32 v108, v108, v230
	v_add_f32_e32 v109, v109, v231
	v_add_f32_e32 v110, v110, v232
	v_add_f32_e32 v111, v111, v233
	v_add_f32_e32 v112, v112, v234
	v_add_f32_e32 v113, v113, v235
	v_add_f32_e32 v114, v114, v236
	v_add_f32_e32 v115, v115, v237

; template <bool SEL, bool GEN>
; DI void attn_step(const KF& kv, const int kb, const int t, const int lane, const bool selbit,
;                   const LAS float* tabh, const half8 (&q)[2][2], f32x4 (&O)[2][4], const float (&nR)[2], float (&l)[2]) {
;     ...
;   f32x4 s[2][2];
; #pragma unroll
;   for (int hp = 0; hp < 2; ++hp) {
;     float nm = nR[hp];
;     if (SEL) nm = selbit ? nm : MASKV;
;     const f32x4 c0 = {nm, nm, nm, nm};
; #pragma unroll
;     for (int kt = 0; kt < 2; ++kt) {
;       s[hp][kt] = MFMA16(kv.k[kt][0], q[hp][0], c0);
;       s[hp][kt] = MFMA16(kv.k[kt][1], q[hp][1], s[hp][kt]);
;     }
;   }
;   if (GEN) {
;     const int d0 = t - kb - fq * 4;
; #pragma unroll
;     for (int kt = 0; kt < 2; ++kt)
; #pragma unroll
;       for (int j = 0; j < 4; ++j) {
;         const int dist = d0 - (kt * 16 + j);
;         const bool bad = SEL ? (dist < 0) : ((unsigned)dist >= 512u);
; DI void attn_phase(const Params& p, const int layer, const int wid_s) {
;     ...
;         for (int si = 0; si < nsteps; ++si) {
;           asm volatile("s_waitcnt vmcnt(1) lgkmcnt(0)" ::: "memory");
;           __builtin_amdgcn_s_barrier();
;           asm volatile("" ::: "memory");
;           RING_ISSUE(si + 2);
;           const int kb = kb0 + si * 32;
;           if (kb > kmax_w || kb < lo_w) continue;
;           if (br == 1 && kb + 31 + 128 <= t0 && __ballot((selmask >> (kb >> 6)) & 1u) == 0ull) continue;
;           LAS unsigned char* slotp = ring + (si % 3) * 8192;
;           KF kv;
; #pragma unroll
;           for (int kt = 0; kt < 2; ++kt)
; #pragma unroll
;             for (int ks = 0; ks < 2; ++ks) kv.k[kt][ks] = *(const LAS half8*)(slotp + kread[kt][ks]);
; #pragma unroll
;           for (int dt = 0; dt < 4; ++dt) kv.v[dt] = *(const LAS half8*)(slotp + vread[dt]);
;           if (br == 1) {
;             const bool bit = (selmask >> (kb >> 6)) & 1u;
;             if (kb + 31 + 128 <= t0) attn_step<true, false>(kv, kb, t, lane, bit, tabh, q, O, nRs, l);
;             else attn_step<true, true>(kv, kb, t, lane, bit, tabh, q, O, nRs, l);
;           } else {
;             const bool gen = (kb + 31 + 128 > t0) || (kb + 512 <= t0 + 15);
;             if (!gen) attn_step<false, false>(kv, kb, t, lane, true, tabh, q, O, nRw, l);
;             else attn_step<false, true>(kv, kb, t, lane, true, tabh, q, O, nRw, l);
;           }
.Lat_yskip3:
	s_bitcmp1_b32 s44, 0
	s_cbranch_scc0 .Lat_yd3
	s_waitcnt lgkmcnt(0)
	v_mfma_f32_16x16x32_f16 v[60:63], v[80:83], v[120:123], v[60:63]
	v_add_f32_e32 v214, v214, v198
	v_add_f32_e32 v215, v215, v199
	v_add_f32_e32 v216, v216, v200
	v_add_f32_e32 v217, v217, v201
	v_add_f32_e32 v214, v214, v202
	v_mfma_f32_16x16x32_f16 v[56:59], v[76:79], v[120:123], v[56:59]
	v_add_f32_e32 v215, v215, v203
	v_add_f32_e32 v216, v216, v204
	v_add_f32_e32 v217, v217, v205
	v_add_f32_e32 v218, v218, v206
	v_add_f32_e32 v219, v219, v207
	v_mfma_f32_16x16x32_f16 v[52:55], v[72:75], v[120:123], v[52:55]
	v_add_f32_e32 v220, v220, v208
	v_add_f32_e32 v221, v221, v209
	v_add_f32_e32 v218, v218, v210
	v_add_f32_e32 v219, v219, v211
	v_add_f32_e32 v220, v220, v212
	v_add_f32_e32 v221, v221, v213
	v_mfma_f32_16x16x32_f16 v[48:51], v[68:71], v[120:123], v[48:51]
	s_add_i32 s8, s45, 64
	s_min_i32 s8, s8, s14
	s_mul_i32 s8, s8, s42
	s_mov_b32 s9, 0
	s_add_i32 m0, s22, 0x1b880
	v_mfma_f32_16x16x32_f16 v[44:47], v[80:83], v[124:127], v[44:47]
	v_lshl_add_u64 v[238:239], v[240:241], 0, s[8:9]
	global_load_lds_dwordx4 v[238:239], off
	s_add_i32 s45, s45, 32
	s_add_i32 s41, s41, -1
	s_cmp_gt_i32 s45, s39
	v_mfma_f32_16x16x32_f16 v[40:43], v[76:79], v[124:127], v[40:43]
	s_cselect_b32 s11, 2, 0
	s_cmp_le_i32 s45, s43
	s_cselect_b32 s10, 2, 0
	s_and_b32 s10, s10, s4
	s_or_b32 s11, s11, s10
	s_lshr_b32 s10, s45, 6
	v_mfma_f32_16x16x32_f16 v[36:39], v[72:75], v[124:127], v[36:39]
	v_bfe_u32 v66, v244, s10, 1
	v_cmp_ne_u32_e32 vcc, 0, v66
	s_cmp_lg_u64 vcc, 0
	s_cselect_b32 s10, 1, 0
	s_lshr_b32 s9, s11, 1
	v_mfma_f32_16x16x32_f16 v[32:35], v[68:71], v[124:127], v[32:35]
	s_or_b32 s10, s10, s9
	s_cmp_le_i32 s45, s15
	s_cselect_b32 s10, s10, 0
	s_cmp_ge_i32 s45, s40
	s_cselect_b32 s10, s10, 0
	s_or_b32 s12, s11, s10
	s_mov_b32 s44, 0
	s_cmp_lg_u32 s41, 0
	s_cbranch_scc1 .Lat_ytop
	s_branch .Lat_yexit
